# K-loop LDS-DMA loads use SGPR-base + 32-bit lane offset addressing (drops 8 VALU 64-bit adds per iteration in all 8 GEMM loops)
# speedup vs baseline: 1.0005x; 1.0005x over previous
.LBB0_538:
	ds_read_b128 v[152:155], v149
	ds_read_b128 v[156:159], v149 offset:1024
	ds_read_b128 v[160:163], v149 offset:2048
	ds_read_b128 v[164:167], v149 offset:3072
	ds_read_b128 v[168:171], v150
	ds_read_b128 v[172:175], v150 offset:1024
	ds_read_b128 v[176:179], v150 offset:2048
	ds_read_b128 v[180:183], v150 offset:3072
	s_add_u32 s40, s38, 0xfffc0080
	s_addc_u32 s41, s39, -1
	s_cmp_eq_u32 s54, 12
	s_cselect_b32 s43, s27, s41
	s_cselect_b32 s42, s50, s40
	s_cselect_b32 s41, s25, s53
	s_cselect_b32 s40, s51, s52
	s_add_i32 m0, s11, 0xc000
	ds_read_b128 v[184:187], v151
	ds_read_b128 v[188:191], v151 offset:1024
	ds_read_b128 v[192:195], v151 offset:2048
	ds_read_b128 v[196:199], v151 offset:3072
	ds_read_b128 v[200:203], v151 offset:4096
	ds_read_b128 v[204:207], v151 offset:5120
	ds_read_b128 v[212:215], v151 offset:6144
	ds_read_b128 v[216:219], v151 offset:7168
	global_load_lds_dwordx4 v136, s[38:39]
	s_add_i32 m0, s11, 0xe000
	s_nop 0
	global_load_lds_dwordx4 v138, s[38:39]
	s_waitcnt vmcnt(8)
	s_waitcnt lgkmcnt(0)
	s_barrier
	s_setprio 1
	s_waitcnt lgkmcnt(0)
	v_mfma_f32_16x16x32_bf16 v[124:127], v[152:155], v[184:187], v[124:127]
	v_mfma_f32_16x16x32_bf16 v[120:123], v[160:163], v[184:187], v[120:123]
	v_mfma_f32_16x16x32_bf16 v[108:111], v[152:155], v[192:195], v[108:111]
	v_mfma_f32_16x16x32_bf16 v[104:107], v[160:163], v[192:195], v[104:107]
	v_mfma_f32_16x16x32_bf16 v[92:95], v[152:155], v[200:203], v[92:95]
	v_mfma_f32_16x16x32_bf16 v[88:91], v[160:163], v[200:203], v[88:91]
	v_mfma_f32_16x16x32_bf16 v[76:79], v[152:155], v[212:215], v[76:79]
	v_mfma_f32_16x16x32_bf16 v[72:75], v[160:163], v[212:215], v[72:75]
	v_mfma_f32_16x16x32_bf16 v[124:127], v[156:159], v[188:191], v[124:127]
	v_mfma_f32_16x16x32_bf16 v[120:123], v[164:167], v[188:191], v[120:123]
	v_mfma_f32_16x16x32_bf16 v[108:111], v[156:159], v[196:199], v[108:111]
	v_mfma_f32_16x16x32_bf16 v[104:107], v[164:167], v[196:199], v[104:107]
	v_mfma_f32_16x16x32_bf16 v[92:95], v[156:159], v[204:207], v[92:95]
	v_mfma_f32_16x16x32_bf16 v[88:91], v[164:167], v[204:207], v[88:91]
	v_mfma_f32_16x16x32_bf16 v[76:79], v[156:159], v[216:219], v[76:79]
	v_mfma_f32_16x16x32_bf16 v[72:75], v[164:167], v[216:219], v[72:75]
	s_setprio 0
	s_setprio 1
	v_mfma_f32_16x16x32_bf16 v[116:119], v[168:171], v[184:187], v[116:119]
	v_mfma_f32_16x16x32_bf16 v[112:115], v[176:179], v[184:187], v[112:115]
	v_mfma_f32_16x16x32_bf16 v[100:103], v[168:171], v[192:195], v[100:103]
	v_mfma_f32_16x16x32_bf16 v[96:99], v[176:179], v[192:195], v[96:99]
	v_mfma_f32_16x16x32_bf16 v[84:87], v[168:171], v[200:203], v[84:87]
	v_mfma_f32_16x16x32_bf16 v[80:83], v[176:179], v[200:203], v[80:83]
	v_mfma_f32_16x16x32_bf16 v[68:71], v[168:171], v[212:215], v[68:71]
	v_mfma_f32_16x16x32_bf16 v[64:67], v[176:179], v[212:215], v[64:67]
	v_mfma_f32_16x16x32_bf16 v[116:119], v[172:175], v[188:191], v[116:119]
	v_mfma_f32_16x16x32_bf16 v[112:115], v[180:183], v[188:191], v[112:115]
	v_mfma_f32_16x16x32_bf16 v[100:103], v[172:175], v[196:199], v[100:103]
	v_mfma_f32_16x16x32_bf16 v[96:99], v[180:183], v[196:199], v[96:99]
	v_mfma_f32_16x16x32_bf16 v[84:87], v[172:175], v[204:207], v[84:87]
	v_mfma_f32_16x16x32_bf16 v[80:83], v[180:183], v[204:207], v[80:83]
	v_mfma_f32_16x16x32_bf16 v[68:71], v[172:175], v[216:219], v[68:71]
	v_mfma_f32_16x16x32_bf16 v[64:67], v[180:183], v[216:219], v[64:67]
	s_setprio 0
	s_barrier
	s_add_i32 s55, s45, s10
	v_lshl_add_u64 v[144:145], s[40:41], 0, v[132:133]
	s_mov_b32 m0, s55
	ds_read_b128 v[184:187], v151 offset:16384
	ds_read_b128 v[188:191], v151 offset:17408
	ds_read_b128 v[192:195], v151 offset:18432
	ds_read_b128 v[196:199], v151 offset:19456
	ds_read_b128 v[200:203], v151 offset:20480
	ds_read_b128 v[204:207], v151 offset:21504
	ds_read_b128 v[212:215], v151 offset:22528
	ds_read_b128 v[216:219], v151 offset:23552
	global_load_lds_dwordx4 v[144:145], off
	s_add_i32 m0, s55, 0x2000
	s_add_u32 s56, s40, 0x40000
	v_lshl_add_u64 v[208:209], s[40:41], 0, v[128:129]
	s_addc_u32 s57, s41, 0
	s_add_i32 s55, s46, s10
	global_load_lds_dwordx4 v[208:209], off
	s_mov_b32 m0, s55
	v_lshl_add_u64 v[222:223], s[42:43], 0, v[130:131]
	global_load_lds_dwordx4 v132, s[56:57]
	s_add_i32 m0, s55, 0x2000
	s_nop 0
	global_load_lds_dwordx4 v128, s[56:57]
	v_lshl_add_u64 v[220:221], s[42:43], 0, v[134:135]
	s_mov_b32 m0, s11
	s_nop 0
	global_load_lds_dwordx4 v[220:221], off
	s_mov_b32 m0, s14
	s_nop 0
	global_load_lds_dwordx4 v[222:223], off
	s_waitcnt vmcnt(8)
	s_waitcnt lgkmcnt(0)
	s_barrier
	s_setprio 1
	s_waitcnt lgkmcnt(0)
	v_mfma_f32_16x16x32_bf16 v[60:63], v[152:155], v[184:187], v[60:63]
	v_mfma_f32_16x16x32_bf16 v[56:59], v[160:163], v[184:187], v[56:59]
	v_mfma_f32_16x16x32_bf16 v[44:47], v[152:155], v[192:195], v[44:47]
	v_mfma_f32_16x16x32_bf16 v[40:43], v[160:163], v[192:195], v[40:43]
	v_mfma_f32_16x16x32_bf16 v[28:31], v[152:155], v[200:203], v[28:31]
	v_mfma_f32_16x16x32_bf16 v[24:27], v[160:163], v[200:203], v[24:27]
	v_mfma_f32_16x16x32_bf16 v[12:15], v[152:155], v[212:215], v[12:15]
	v_mfma_f32_16x16x32_bf16 v[8:11], v[160:163], v[212:215], v[8:11]
	v_mfma_f32_16x16x32_bf16 v[60:63], v[156:159], v[188:191], v[60:63]
	v_mfma_f32_16x16x32_bf16 v[56:59], v[164:167], v[188:191], v[56:59]
	v_mfma_f32_16x16x32_bf16 v[44:47], v[156:159], v[196:199], v[44:47]
	v_mfma_f32_16x16x32_bf16 v[40:43], v[164:167], v[196:199], v[40:43]
	v_mfma_f32_16x16x32_bf16 v[28:31], v[156:159], v[204:207], v[28:31]
	v_mfma_f32_16x16x32_bf16 v[24:27], v[164:167], v[204:207], v[24:27]
	v_mfma_f32_16x16x32_bf16 v[12:15], v[156:159], v[216:219], v[12:15]
	v_mfma_f32_16x16x32_bf16 v[8:11], v[164:167], v[216:219], v[8:11]
	s_setprio 0
	s_setprio 1
	v_mfma_f32_16x16x32_bf16 v[52:55], v[168:171], v[184:187], v[52:55]
	v_mfma_f32_16x16x32_bf16 v[48:51], v[176:179], v[184:187], v[48:51]
	v_mfma_f32_16x16x32_bf16 v[36:39], v[168:171], v[192:195], v[36:39]
	v_mfma_f32_16x16x32_bf16 v[32:35], v[176:179], v[192:195], v[32:35]
	v_mfma_f32_16x16x32_bf16 v[20:23], v[168:171], v[200:203], v[20:23]
	v_mfma_f32_16x16x32_bf16 v[16:19], v[176:179], v[200:203], v[16:19]
	v_mfma_f32_16x16x32_bf16 v[4:7], v[168:171], v[212:215], v[4:7]
	v_mfma_f32_16x16x32_bf16 v[0:3], v[176:179], v[212:215], v[0:3]
	v_mfma_f32_16x16x32_bf16 v[52:55], v[172:175], v[188:191], v[52:55]
	v_mfma_f32_16x16x32_bf16 v[48:51], v[180:183], v[188:191], v[48:51]
	v_mfma_f32_16x16x32_bf16 v[36:39], v[172:175], v[196:199], v[36:39]
	v_mfma_f32_16x16x32_bf16 v[32:35], v[180:183], v[196:199], v[32:35]
	v_mfma_f32_16x16x32_bf16 v[20:23], v[172:175], v[204:207], v[20:23]
	v_mfma_f32_16x16x32_bf16 v[16:19], v[180:183], v[204:207], v[16:19]
	v_mfma_f32_16x16x32_bf16 v[4:7], v[172:175], v[216:219], v[4:7]
	v_mfma_f32_16x16x32_bf16 v[0:3], v[180:183], v[216:219], v[0:3]
	s_setprio 0
	s_barrier
	s_add_i32 s55, 0, 0x18000
	s_add_i32 s56, 0, 0x1c000
	v_add_u32_e32 v164, s55, v147
	v_add_u32_e32 v180, s56, v147
	ds_read_b128 v[152:155], v164
	ds_read_b128 v[156:159], v164 offset:1024
	ds_read_b128 v[160:163], v164 offset:2048
	ds_read_b128 v[164:167], v164 offset:3072
	ds_read_b128 v[168:171], v180
	ds_read_b128 v[172:175], v180 offset:1024
	ds_read_b128 v[176:179], v180 offset:2048
	ds_read_b128 v[180:183], v180 offset:3072
	s_add_u32 s42, s42, 0x40000
	s_addc_u32 s43, s43, 0
	s_mov_b32 m0, s15
	ds_read_b128 v[184:187], v151 offset:32768
	ds_read_b128 v[188:191], v151 offset:33792
	ds_read_b128 v[192:195], v151 offset:34816
	ds_read_b128 v[196:199], v151 offset:35840
	ds_read_b128 v[200:203], v151 offset:36864
	ds_read_b128 v[204:207], v151 offset:37888
	ds_read_b128 v[212:215], v151 offset:38912
	ds_read_b128 v[216:219], v151 offset:39936
	global_load_lds_dwordx4 v134, s[42:43]
	s_mov_b32 m0, s28
	s_nop 0
	global_load_lds_dwordx4 v130, s[42:43]
	s_waitcnt vmcnt(8)
	s_waitcnt lgkmcnt(0)
	s_barrier
	s_setprio 1
	s_waitcnt lgkmcnt(0)
	v_mfma_f32_16x16x32_bf16 v[124:127], v[152:155], v[184:187], v[124:127]
	v_mfma_f32_16x16x32_bf16 v[120:123], v[160:163], v[184:187], v[120:123]
	v_mfma_f32_16x16x32_bf16 v[108:111], v[152:155], v[192:195], v[108:111]
	v_mfma_f32_16x16x32_bf16 v[104:107], v[160:163], v[192:195], v[104:107]
	v_mfma_f32_16x16x32_bf16 v[92:95], v[152:155], v[200:203], v[92:95]
	v_mfma_f32_16x16x32_bf16 v[88:91], v[160:163], v[200:203], v[88:91]
	v_mfma_f32_16x16x32_bf16 v[76:79], v[152:155], v[212:215], v[76:79]
	v_mfma_f32_16x16x32_bf16 v[72:75], v[160:163], v[212:215], v[72:75]
	v_mfma_f32_16x16x32_bf16 v[124:127], v[156:159], v[188:191], v[124:127]
	v_mfma_f32_16x16x32_bf16 v[120:123], v[164:167], v[188:191], v[120:123]
	v_mfma_f32_16x16x32_bf16 v[108:111], v[156:159], v[196:199], v[108:111]
	v_mfma_f32_16x16x32_bf16 v[104:107], v[164:167], v[196:199], v[104:107]
	v_mfma_f32_16x16x32_bf16 v[92:95], v[156:159], v[204:207], v[92:95]
	v_mfma_f32_16x16x32_bf16 v[88:91], v[164:167], v[204:207], v[88:91]
	v_mfma_f32_16x16x32_bf16 v[76:79], v[156:159], v[216:219], v[76:79]
	v_mfma_f32_16x16x32_bf16 v[72:75], v[164:167], v[216:219], v[72:75]
	s_setprio 0
	s_setprio 1
	v_mfma_f32_16x16x32_bf16 v[116:119], v[168:171], v[184:187], v[116:119]
	v_mfma_f32_16x16x32_bf16 v[112:115], v[176:179], v[184:187], v[112:115]
	v_mfma_f32_16x16x32_bf16 v[100:103], v[168:171], v[192:195], v[100:103]
	v_mfma_f32_16x16x32_bf16 v[96:99], v[176:179], v[192:195], v[96:99]
	v_mfma_f32_16x16x32_bf16 v[84:87], v[168:171], v[200:203], v[84:87]
	v_mfma_f32_16x16x32_bf16 v[80:83], v[176:179], v[200:203], v[80:83]
	v_mfma_f32_16x16x32_bf16 v[68:71], v[168:171], v[212:215], v[68:71]
	v_mfma_f32_16x16x32_bf16 v[64:67], v[176:179], v[212:215], v[64:67]
	v_mfma_f32_16x16x32_bf16 v[116:119], v[172:175], v[188:191], v[116:119]
	v_mfma_f32_16x16x32_bf16 v[112:115], v[180:183], v[188:191], v[112:115]
	v_mfma_f32_16x16x32_bf16 v[100:103], v[172:175], v[196:199], v[100:103]
	v_mfma_f32_16x16x32_bf16 v[96:99], v[180:183], v[196:199], v[96:99]
	v_mfma_f32_16x16x32_bf16 v[84:87], v[172:175], v[204:207], v[84:87]
	v_mfma_f32_16x16x32_bf16 v[80:83], v[180:183], v[204:207], v[80:83]
	v_mfma_f32_16x16x32_bf16 v[68:71], v[172:175], v[216:219], v[68:71]
	v_mfma_f32_16x16x32_bf16 v[64:67], v[180:183], v[216:219], v[64:67]
	s_setprio 0
	s_barrier
	s_add_i32 s42, s55, s10
	v_lshl_add_u64 v[144:145], v[144:145], 0, s[4:5]
	s_mov_b32 m0, s42
	ds_read_b128 v[184:187], v151 offset:49152
	ds_read_b128 v[188:191], v151 offset:50176
	ds_read_b128 v[192:195], v151 offset:51200
	ds_read_b128 v[196:199], v151 offset:52224
	ds_read_b128 v[200:203], v151 offset:53248
	ds_read_b128 v[204:207], v151 offset:54272
	ds_read_b128 v[212:215], v151 offset:55296
	ds_read_b128 v[216:219], v151 offset:56320
	global_load_lds_dwordx4 v[144:145], off
	s_add_i32 m0, s42, 0x2000
	s_add_u32 s40, s40, 0x40080
	v_lshl_add_u64 v[144:145], v[208:209], 0, s[4:5]
	s_addc_u32 s41, s41, 0
	s_add_i32 s42, s56, s10
	global_load_lds_dwordx4 v[144:145], off
	s_mov_b32 m0, s42
	s_nop 0
	global_load_lds_dwordx4 v132, s[40:41]
	s_add_i32 m0, s42, 0x2000
	s_nop 0
	global_load_lds_dwordx4 v128, s[40:41]
	v_lshl_add_u64 v[144:145], v[220:221], 0, s[4:5]
	s_mov_b32 m0, s29
	s_nop 0
	global_load_lds_dwordx4 v[144:145], off
	v_lshl_add_u64 v[144:145], v[222:223], 0, s[4:5]
	s_mov_b32 m0, s33
	s_nop 0
	global_load_lds_dwordx4 v[144:145], off
	s_waitcnt vmcnt(8)
	s_waitcnt lgkmcnt(0)
	s_barrier
	s_setprio 1
	s_waitcnt lgkmcnt(0)
	v_mfma_f32_16x16x32_bf16 v[60:63], v[152:155], v[184:187], v[60:63]
	v_mfma_f32_16x16x32_bf16 v[56:59], v[160:163], v[184:187], v[56:59]
	v_mfma_f32_16x16x32_bf16 v[44:47], v[152:155], v[192:195], v[44:47]
	v_mfma_f32_16x16x32_bf16 v[40:43], v[160:163], v[192:195], v[40:43]
	v_mfma_f32_16x16x32_bf16 v[28:31], v[152:155], v[200:203], v[28:31]
	v_mfma_f32_16x16x32_bf16 v[24:27], v[160:163], v[200:203], v[24:27]
	v_mfma_f32_16x16x32_bf16 v[12:15], v[152:155], v[212:215], v[12:15]
	v_mfma_f32_16x16x32_bf16 v[8:11], v[160:163], v[212:215], v[8:11]
	v_mfma_f32_16x16x32_bf16 v[60:63], v[156:159], v[188:191], v[60:63]
	v_mfma_f32_16x16x32_bf16 v[56:59], v[164:167], v[188:191], v[56:59]
	v_mfma_f32_16x16x32_bf16 v[44:47], v[156:159], v[196:199], v[44:47]
	v_mfma_f32_16x16x32_bf16 v[40:43], v[164:167], v[196:199], v[40:43]
	v_mfma_f32_16x16x32_bf16 v[28:31], v[156:159], v[204:207], v[28:31]
	v_mfma_f32_16x16x32_bf16 v[24:27], v[164:167], v[204:207], v[24:27]
	v_mfma_f32_16x16x32_bf16 v[12:15], v[156:159], v[216:219], v[12:15]
	v_mfma_f32_16x16x32_bf16 v[8:11], v[164:167], v[216:219], v[8:11]
	s_setprio 0
	s_setprio 1
	v_mfma_f32_16x16x32_bf16 v[52:55], v[168:171], v[184:187], v[52:55]
	v_mfma_f32_16x16x32_bf16 v[48:51], v[176:179], v[184:187], v[48:51]
	v_mfma_f32_16x16x32_bf16 v[36:39], v[168:171], v[192:195], v[36:39]
	v_mfma_f32_16x16x32_bf16 v[32:35], v[176:179], v[192:195], v[32:35]
	v_mfma_f32_16x16x32_bf16 v[20:23], v[168:171], v[200:203], v[20:23]
	v_mfma_f32_16x16x32_bf16 v[16:19], v[176:179], v[200:203], v[16:19]
	v_mfma_f32_16x16x32_bf16 v[4:7], v[168:171], v[212:215], v[4:7]
	v_mfma_f32_16x16x32_bf16 v[0:3], v[176:179], v[212:215], v[0:3]
	v_mfma_f32_16x16x32_bf16 v[52:55], v[172:175], v[188:191], v[52:55]
	v_mfma_f32_16x16x32_bf16 v[48:51], v[180:183], v[188:191], v[48:51]
	v_mfma_f32_16x16x32_bf16 v[36:39], v[172:175], v[196:199], v[36:39]
	v_mfma_f32_16x16x32_bf16 v[32:35], v[180:183], v[196:199], v[32:35]
	v_mfma_f32_16x16x32_bf16 v[20:23], v[172:175], v[204:207], v[20:23]
	v_mfma_f32_16x16x32_bf16 v[16:19], v[180:183], v[204:207], v[16:19]
	v_mfma_f32_16x16x32_bf16 v[4:7], v[172:175], v[216:219], v[4:7]
	v_mfma_f32_16x16x32_bf16 v[0:3], v[180:183], v[216:219], v[0:3]
	s_setprio 0
	s_barrier
	s_add_i32 s54, s54, 2
	s_add_u32 s38, s38, 0x100
	s_addc_u32 s39, s39, 0
	s_add_u32 s52, s52, 0x100
	s_addc_u32 s53, s53, 0
	s_cmp_gt_u32 s54, 13
	s_cbranch_scc0 .LBB0_538
	s_and_b64 vcc, exec, s[8:9]
	s_cbranch_vccz .LBB0_541
	s_barrier

.LBB0_617:
	ds_read_b128 v[32:35], v186
	ds_read_b128 v[36:39], v186 offset:1024
	ds_read_b128 v[40:43], v186 offset:2048
	ds_read_b128 v[44:47], v186 offset:3072
	ds_read_b128 v[48:51], v187
	ds_read_b128 v[52:55], v187 offset:1024
	ds_read_b128 v[56:59], v187 offset:2048
	ds_read_b128 v[60:63], v187 offset:3072
	s_add_u32 s38, s2, 0x100
	s_addc_u32 s39, s3, 0
	s_cmp_eq_u32 s52, 40
	s_cselect_b32 s43, s7, s39
	s_cselect_b32 s42, s6, s38
	s_cselect_b32 s41, s37, s51
	s_cselect_b32 s40, s36, s1
	s_add_i32 m0, s11, 0xc000
	ds_read_b128 v[176:179], v188
	ds_read_b128 v[190:193], v188 offset:1024
	ds_read_b128 v[194:197], v188 offset:2048
	ds_read_b128 v[198:201], v188 offset:3072
	ds_read_b128 v[202:205], v188 offset:4096
	ds_read_b128 v[206:209], v188 offset:5120
	ds_read_b128 v[212:215], v188 offset:6144
	ds_read_b128 v[216:219], v188 offset:7168
	global_load_lds_dwordx4 v168, s[2:3]
	s_add_i32 m0, s11, 0xe000
	s_nop 0
	global_load_lds_dwordx4 v170, s[2:3]
	s_waitcnt vmcnt(8)
	s_waitcnt lgkmcnt(0)
	s_barrier
	s_setprio 1
	s_waitcnt lgkmcnt(0)
	v_mfma_f32_16x16x32_bf16 v[156:159], v[32:35], v[176:179], v[156:159]
	v_mfma_f32_16x16x32_bf16 v[152:155], v[40:43], v[176:179], v[152:155]
	v_mfma_f32_16x16x32_bf16 v[140:143], v[32:35], v[194:197], v[140:143]
	v_mfma_f32_16x16x32_bf16 v[136:139], v[40:43], v[194:197], v[136:139]
	v_mfma_f32_16x16x32_bf16 v[124:127], v[32:35], v[202:205], v[124:127]
	v_mfma_f32_16x16x32_bf16 v[120:123], v[40:43], v[202:205], v[120:123]
	v_mfma_f32_16x16x32_bf16 v[108:111], v[32:35], v[212:215], v[108:111]
	v_mfma_f32_16x16x32_bf16 v[104:107], v[40:43], v[212:215], v[104:107]
	v_mfma_f32_16x16x32_bf16 v[156:159], v[36:39], v[190:193], v[156:159]
	v_mfma_f32_16x16x32_bf16 v[152:155], v[44:47], v[190:193], v[152:155]
	v_mfma_f32_16x16x32_bf16 v[140:143], v[36:39], v[198:201], v[140:143]
	v_mfma_f32_16x16x32_bf16 v[136:139], v[44:47], v[198:201], v[136:139]
	v_mfma_f32_16x16x32_bf16 v[124:127], v[36:39], v[206:209], v[124:127]
	v_mfma_f32_16x16x32_bf16 v[120:123], v[44:47], v[206:209], v[120:123]
	v_mfma_f32_16x16x32_bf16 v[108:111], v[36:39], v[216:219], v[108:111]
	v_mfma_f32_16x16x32_bf16 v[104:107], v[44:47], v[216:219], v[104:107]
	s_setprio 0
	s_setprio 1
	v_mfma_f32_16x16x32_bf16 v[148:151], v[48:51], v[176:179], v[148:151]
	v_mfma_f32_16x16x32_bf16 v[144:147], v[56:59], v[176:179], v[144:147]
	v_mfma_f32_16x16x32_bf16 v[132:135], v[48:51], v[194:197], v[132:135]
	v_mfma_f32_16x16x32_bf16 v[128:131], v[56:59], v[194:197], v[128:131]
	v_mfma_f32_16x16x32_bf16 v[116:119], v[48:51], v[202:205], v[116:119]
	v_mfma_f32_16x16x32_bf16 v[112:115], v[56:59], v[202:205], v[112:115]
	v_mfma_f32_16x16x32_bf16 v[100:103], v[48:51], v[212:215], v[100:103]
	v_mfma_f32_16x16x32_bf16 v[96:99], v[56:59], v[212:215], v[96:99]
	v_mfma_f32_16x16x32_bf16 v[148:151], v[52:55], v[190:193], v[148:151]
	v_mfma_f32_16x16x32_bf16 v[144:147], v[60:63], v[190:193], v[144:147]
	v_mfma_f32_16x16x32_bf16 v[132:135], v[52:55], v[198:201], v[132:135]
	v_mfma_f32_16x16x32_bf16 v[128:131], v[60:63], v[198:201], v[128:131]
	v_mfma_f32_16x16x32_bf16 v[116:119], v[52:55], v[206:209], v[116:119]
	v_mfma_f32_16x16x32_bf16 v[112:115], v[60:63], v[206:209], v[112:115]
	v_mfma_f32_16x16x32_bf16 v[100:103], v[52:55], v[216:219], v[100:103]
	v_mfma_f32_16x16x32_bf16 v[96:99], v[60:63], v[216:219], v[96:99]
	s_setprio 0
	s_barrier
	s_add_i32 s2, s46, s10
	v_lshl_add_u64 v[180:181], s[40:41], 0, v[162:163]
	s_mov_b32 m0, s2
	ds_read_b128 v[176:179], v188 offset:16384
	ds_read_b128 v[190:193], v188 offset:17408
	ds_read_b128 v[194:197], v188 offset:18432
	ds_read_b128 v[198:201], v188 offset:19456
	ds_read_b128 v[202:205], v188 offset:20480
	ds_read_b128 v[206:209], v188 offset:21504
	ds_read_b128 v[212:215], v188 offset:22528
	ds_read_b128 v[216:219], v188 offset:23552
	global_load_lds_dwordx4 v[180:181], off
	s_add_i32 m0, s2, 0x2000
	s_add_u32 s2, s40, 0xb0000
	v_lshl_add_u64 v[228:229], s[40:41], 0, v[166:167]
	s_addc_u32 s3, s41, 0
	s_add_i32 s53, s47, s10
	global_load_lds_dwordx4 v[228:229], off
	s_mov_b32 m0, s53
	v_lshl_add_u64 v[230:231], s[42:43], 0, v[160:161]
	global_load_lds_dwordx4 v162, s[2:3]
	s_add_i32 m0, s53, 0x2000
	v_lshl_add_u64 v[232:233], s[42:43], 0, v[164:165]
	global_load_lds_dwordx4 v166, s[2:3]
	s_mov_b32 m0, s11
	s_nop 0
	global_load_lds_dwordx4 v[230:231], off
	s_mov_b32 m0, s14
	s_nop 0
	global_load_lds_dwordx4 v[232:233], off
	s_waitcnt vmcnt(8)
	s_waitcnt lgkmcnt(0)
	s_barrier
	s_setprio 1
	s_waitcnt lgkmcnt(0)
	v_mfma_f32_16x16x32_bf16 v[92:95], v[32:35], v[176:179], v[92:95]
	v_mfma_f32_16x16x32_bf16 v[88:91], v[40:43], v[176:179], v[88:91]
	v_mfma_f32_16x16x32_bf16 v[76:79], v[32:35], v[194:197], v[76:79]
	v_mfma_f32_16x16x32_bf16 v[72:75], v[40:43], v[194:197], v[72:75]
	v_mfma_f32_16x16x32_bf16 v[28:31], v[32:35], v[202:205], v[28:31]
	v_mfma_f32_16x16x32_bf16 v[24:27], v[40:43], v[202:205], v[24:27]
	v_mfma_f32_16x16x32_bf16 v[12:15], v[32:35], v[212:215], v[12:15]
	v_mfma_f32_16x16x32_bf16 v[8:11], v[40:43], v[212:215], v[8:11]
	v_mfma_f32_16x16x32_bf16 v[92:95], v[36:39], v[190:193], v[92:95]
	v_mfma_f32_16x16x32_bf16 v[88:91], v[44:47], v[190:193], v[88:91]
	v_mfma_f32_16x16x32_bf16 v[76:79], v[36:39], v[198:201], v[76:79]
	v_mfma_f32_16x16x32_bf16 v[72:75], v[44:47], v[198:201], v[72:75]
	v_mfma_f32_16x16x32_bf16 v[28:31], v[36:39], v[206:209], v[28:31]
	v_mfma_f32_16x16x32_bf16 v[24:27], v[44:47], v[206:209], v[24:27]
	v_mfma_f32_16x16x32_bf16 v[12:15], v[36:39], v[216:219], v[12:15]
	v_mfma_f32_16x16x32_bf16 v[8:11], v[44:47], v[216:219], v[8:11]
	s_setprio 0
	s_setprio 1
	v_mfma_f32_16x16x32_bf16 v[20:23], v[48:51], v[202:205], v[20:23]
	v_mfma_f32_16x16x32_bf16 v[16:19], v[56:59], v[202:205], v[16:19]
	v_mfma_f32_16x16x32_bf16 v[4:7], v[48:51], v[212:215], v[4:7]
	v_mfma_f32_16x16x32_bf16 v[0:3], v[56:59], v[212:215], v[0:3]
	v_mfma_f32_16x16x32_bf16 v[32:35], v[48:51], v[176:179], v[84:87]
	v_mfma_f32_16x16x32_bf16 v[36:39], v[56:59], v[176:179], v[80:83]
	v_mfma_f32_16x16x32_bf16 v[40:43], v[48:51], v[194:197], v[68:71]
	v_mfma_f32_16x16x32_bf16 v[44:47], v[56:59], v[194:197], v[64:67]
	v_mfma_f32_16x16x32_bf16 v[20:23], v[52:55], v[206:209], v[20:23]
	v_mfma_f32_16x16x32_bf16 v[16:19], v[60:63], v[206:209], v[16:19]
	v_mfma_f32_16x16x32_bf16 v[4:7], v[52:55], v[216:219], v[4:7]
	v_mfma_f32_16x16x32_bf16 v[0:3], v[60:63], v[216:219], v[0:3]
	v_mfma_f32_16x16x32_bf16 v[32:35], v[52:55], v[190:193], v[32:35]
	v_mfma_f32_16x16x32_bf16 v[36:39], v[60:63], v[190:193], v[36:39]
	v_mfma_f32_16x16x32_bf16 v[40:43], v[52:55], v[198:201], v[40:43]
	v_mfma_f32_16x16x32_bf16 v[44:47], v[60:63], v[198:201], v[44:47]
	s_setprio 0
	s_barrier
	s_add_i32 s53, 0, 0x18000
	s_add_i32 s54, 0, 0x1c000
	v_add_u32_e32 v60, s53, v183
	v_add_u32_e32 v64, s54, v183
	ds_read_b128 v[48:51], v60
	ds_read_b128 v[52:55], v60 offset:1024
	ds_read_b128 v[56:59], v60 offset:2048
	ds_read_b128 v[60:63], v60 offset:3072
	ds_read_b128 v[176:179], v64
	ds_read_b128 v[190:193], v64 offset:1024
	ds_read_b128 v[194:197], v64 offset:2048
	ds_read_b128 v[198:201], v64 offset:3072
	s_add_u32 s2, s42, 0xb0000
	s_addc_u32 s3, s43, 0
	s_mov_b32 m0, s15
	ds_read_b128 v[64:67], v188 offset:32768
	ds_read_b128 v[68:71], v188 offset:33792
	ds_read_b128 v[80:83], v188 offset:34816
	ds_read_b128 v[84:87], v188 offset:35840
	ds_read_b128 v[202:205], v188 offset:36864
	ds_read_b128 v[206:209], v188 offset:37888
	ds_read_b128 v[212:215], v188 offset:38912
	ds_read_b128 v[216:219], v188 offset:39936
	global_load_lds_dwordx4 v160, s[2:3]
	s_mov_b32 m0, s28
	s_nop 0
	global_load_lds_dwordx4 v164, s[2:3]
	s_waitcnt vmcnt(8)
	s_waitcnt lgkmcnt(0)
	s_barrier
	s_setprio 1
	s_waitcnt lgkmcnt(0)
	v_mfma_f32_16x16x32_bf16 v[156:159], v[48:51], v[64:67], v[156:159]
	v_mfma_f32_16x16x32_bf16 v[152:155], v[56:59], v[64:67], v[152:155]
	v_mfma_f32_16x16x32_bf16 v[140:143], v[48:51], v[80:83], v[140:143]
	v_mfma_f32_16x16x32_bf16 v[136:139], v[56:59], v[80:83], v[136:139]
	v_mfma_f32_16x16x32_bf16 v[124:127], v[48:51], v[202:205], v[124:127]
	v_mfma_f32_16x16x32_bf16 v[120:123], v[56:59], v[202:205], v[120:123]
	v_mfma_f32_16x16x32_bf16 v[108:111], v[48:51], v[212:215], v[108:111]
	v_mfma_f32_16x16x32_bf16 v[104:107], v[56:59], v[212:215], v[104:107]
	v_mfma_f32_16x16x32_bf16 v[156:159], v[52:55], v[68:71], v[156:159]
	v_mfma_f32_16x16x32_bf16 v[152:155], v[60:63], v[68:71], v[152:155]
	v_mfma_f32_16x16x32_bf16 v[140:143], v[52:55], v[84:87], v[140:143]
	v_mfma_f32_16x16x32_bf16 v[136:139], v[60:63], v[84:87], v[136:139]
	v_mfma_f32_16x16x32_bf16 v[124:127], v[52:55], v[206:209], v[124:127]
	v_mfma_f32_16x16x32_bf16 v[120:123], v[60:63], v[206:209], v[120:123]
	v_mfma_f32_16x16x32_bf16 v[108:111], v[52:55], v[216:219], v[108:111]
	v_mfma_f32_16x16x32_bf16 v[104:107], v[60:63], v[216:219], v[104:107]
	s_setprio 0
	s_setprio 1
	v_mfma_f32_16x16x32_bf16 v[148:151], v[176:179], v[64:67], v[148:151]
	v_mfma_f32_16x16x32_bf16 v[64:67], v[194:197], v[64:67], v[144:147]
	v_mfma_f32_16x16x32_bf16 v[144:147], v[198:201], v[68:71], v[64:67]
	v_mfma_f32_16x16x32_bf16 v[64:67], v[176:179], v[80:83], v[132:135]
	v_mfma_f32_16x16x32_bf16 v[132:135], v[190:193], v[84:87], v[64:67]
	v_mfma_f32_16x16x32_bf16 v[64:67], v[194:197], v[80:83], v[128:131]
	v_mfma_f32_16x16x32_bf16 v[128:131], v[198:201], v[84:87], v[64:67]
	v_mfma_f32_16x16x32_bf16 v[64:67], v[176:179], v[202:205], v[116:119]
	v_mfma_f32_16x16x32_bf16 v[116:119], v[190:193], v[206:209], v[64:67]
	v_mfma_f32_16x16x32_bf16 v[64:67], v[194:197], v[202:205], v[112:115]
	v_mfma_f32_16x16x32_bf16 v[112:115], v[198:201], v[206:209], v[64:67]
	v_mfma_f32_16x16x32_bf16 v[64:67], v[176:179], v[212:215], v[100:103]
	v_mfma_f32_16x16x32_bf16 v[100:103], v[190:193], v[216:219], v[64:67]
	v_mfma_f32_16x16x32_bf16 v[64:67], v[194:197], v[212:215], v[96:99]
	v_mfma_f32_16x16x32_bf16 v[148:151], v[190:193], v[68:71], v[148:151]
	v_mfma_f32_16x16x32_bf16 v[96:99], v[198:201], v[216:219], v[64:67]
	s_setprio 0
	s_barrier
	s_add_i32 s2, s53, s10
	v_lshl_add_u64 v[80:81], v[180:181], 0, s[26:27]
	s_mov_b32 m0, s2
	s_nop 0
	ds_read_b128 v[64:67], v188 offset:49152
	ds_read_b128 v[68:71], v188 offset:50176
	ds_read_b128 v[202:205], v188 offset:51200
	ds_read_b128 v[206:209], v188 offset:52224
	ds_read_b128 v[212:215], v188 offset:53248
	ds_read_b128 v[216:219], v188 offset:54272
	ds_read_b128 v[220:223], v188 offset:55296
	ds_read_b128 v[224:227], v188 offset:56320
	global_load_lds_dwordx4 v[80:81], off
	s_add_i32 m0, s2, 0x2000
	s_add_u32 s2, s40, 0xb0080
	v_lshl_add_u64 v[80:81], v[228:229], 0, s[26:27]
	s_addc_u32 s3, s41, 0
	s_add_i32 s40, s54, s10
	global_load_lds_dwordx4 v[80:81], off
	s_mov_b32 m0, s40
	s_nop 0
	global_load_lds_dwordx4 v162, s[2:3]
	s_add_i32 m0, s40, 0x2000
	s_nop 0
	global_load_lds_dwordx4 v166, s[2:3]
	v_lshl_add_u64 v[80:81], v[230:231], 0, s[26:27]
	s_mov_b32 m0, s33
	s_nop 0
	global_load_lds_dwordx4 v[80:81], off
	v_lshl_add_u64 v[80:81], v[232:233], 0, s[26:27]
	s_mov_b32 m0, s44
	s_nop 0
	global_load_lds_dwordx4 v[80:81], off
	s_waitcnt vmcnt(8)
	s_waitcnt lgkmcnt(0)
	s_barrier
	s_setprio 1
	s_waitcnt lgkmcnt(0)
	v_mfma_f32_16x16x32_bf16 v[80:83], v[48:51], v[64:67], v[92:95]
	v_mfma_f32_16x16x32_bf16 v[92:95], v[52:55], v[68:71], v[80:83]
	v_mfma_f32_16x16x32_bf16 v[80:83], v[56:59], v[64:67], v[88:91]
	v_mfma_f32_16x16x32_bf16 v[76:79], v[48:51], v[202:205], v[76:79]
	v_mfma_f32_16x16x32_bf16 v[72:75], v[56:59], v[202:205], v[72:75]
	v_mfma_f32_16x16x32_bf16 v[28:31], v[48:51], v[212:215], v[28:31]
	v_mfma_f32_16x16x32_bf16 v[24:27], v[56:59], v[212:215], v[24:27]
	v_mfma_f32_16x16x32_bf16 v[12:15], v[48:51], v[220:223], v[12:15]
	v_mfma_f32_16x16x32_bf16 v[8:11], v[56:59], v[220:223], v[8:11]
	v_mfma_f32_16x16x32_bf16 v[88:91], v[60:63], v[68:71], v[80:83]
	v_mfma_f32_16x16x32_bf16 v[76:79], v[52:55], v[206:209], v[76:79]
	v_mfma_f32_16x16x32_bf16 v[72:75], v[60:63], v[206:209], v[72:75]
	v_mfma_f32_16x16x32_bf16 v[28:31], v[52:55], v[216:219], v[28:31]
	v_mfma_f32_16x16x32_bf16 v[24:27], v[60:63], v[216:219], v[24:27]
	v_mfma_f32_16x16x32_bf16 v[12:15], v[52:55], v[224:227], v[12:15]
	v_mfma_f32_16x16x32_bf16 v[8:11], v[60:63], v[224:227], v[8:11]
	s_setprio 0
	s_setprio 1
	v_mfma_f32_16x16x32_bf16 v[32:35], v[176:179], v[64:67], v[32:35]
	v_mfma_f32_16x16x32_bf16 v[84:87], v[190:193], v[68:71], v[32:35]
	v_mfma_f32_16x16x32_bf16 v[32:35], v[194:197], v[64:67], v[36:39]
	v_mfma_f32_16x16x32_bf16 v[80:83], v[198:201], v[68:71], v[32:35]
	v_mfma_f32_16x16x32_bf16 v[32:35], v[176:179], v[202:205], v[40:43]
	v_mfma_f32_16x16x32_bf16 v[68:71], v[190:193], v[206:209], v[32:35]
	v_mfma_f32_16x16x32_bf16 v[32:35], v[194:197], v[202:205], v[44:47]
	v_mfma_f32_16x16x32_bf16 v[20:23], v[176:179], v[212:215], v[20:23]
	v_mfma_f32_16x16x32_bf16 v[16:19], v[194:197], v[212:215], v[16:19]
	v_mfma_f32_16x16x32_bf16 v[4:7], v[176:179], v[220:223], v[4:7]
	v_mfma_f32_16x16x32_bf16 v[0:3], v[194:197], v[220:223], v[0:3]
	v_mfma_f32_16x16x32_bf16 v[64:67], v[198:201], v[206:209], v[32:35]
	v_mfma_f32_16x16x32_bf16 v[20:23], v[190:193], v[216:219], v[20:23]
	v_mfma_f32_16x16x32_bf16 v[16:19], v[198:201], v[216:219], v[16:19]
	v_mfma_f32_16x16x32_bf16 v[4:7], v[190:193], v[224:227], v[4:7]
	v_mfma_f32_16x16x32_bf16 v[0:3], v[198:201], v[224:227], v[0:3]
	s_setprio 0
	s_barrier
	s_add_i32 s52, s52, 2
	s_add_u32 s1, s1, 0x100
	s_addc_u32 s51, s51, 0
	s_cmp_gt_u32 s52, 41
	s_mov_b64 s[2:3], s[38:39]
	s_cbranch_scc0 .LBB0_617
	s_and_b64 vcc, exec, s[34:35]
	s_cbranch_vccz .LBB0_620
	s_barrier

.LBB0_704:
	ds_read_b128 v[128:131], v214
	ds_read_b128 v[132:135], v214 offset:1024
	ds_read_b128 v[136:139], v214 offset:2048
	ds_read_b128 v[140:143], v214 offset:3072
	ds_read_b128 v[144:147], v215
	ds_read_b128 v[148:151], v215 offset:1024
	ds_read_b128 v[168:171], v215 offset:2048
	ds_read_b128 v[172:175], v215 offset:3072
	s_add_u32 s6, s4, 0xfffc0080
	s_addc_u32 s7, s5, -1
	s_cmp_eq_u32 s57, 12
	s_cselect_b32 s63, s3, s7
	s_cselect_b32 s62, s11, s6
	s_cselect_b32 s7, s14, s55
	s_cselect_b32 s6, s15, s28
	s_add_i32 m0, s64, 0xc000
	ds_read_b128 v[176:179], v216
	ds_read_b128 v[180:183], v216 offset:1024
	ds_read_b128 v[184:187], v216 offset:2048
	ds_read_b128 v[188:191], v216 offset:3072
	ds_read_b128 v[192:195], v216 offset:4096
	ds_read_b128 v[196:199], v216 offset:5120
	ds_read_b128 v[200:203], v216 offset:6144
	ds_read_b128 v[204:207], v216 offset:7168
	global_load_lds_dwordx4 v160, s[4:5]
	s_add_i32 m0, s64, 0xe000
	s_nop 0
	global_load_lds_dwordx4 v162, s[4:5]
	s_waitcnt vmcnt(8)
	s_waitcnt lgkmcnt(0)
	s_barrier
	s_setprio 1
	s_waitcnt lgkmcnt(0)
	v_mfma_f32_16x16x32_bf16 v[124:127], v[128:131], v[176:179], v[124:127]
	v_mfma_f32_16x16x32_bf16 v[120:123], v[136:139], v[176:179], v[120:123]
	v_mfma_f32_16x16x32_bf16 v[116:119], v[128:131], v[184:187], v[116:119]
	v_mfma_f32_16x16x32_bf16 v[112:115], v[136:139], v[184:187], v[112:115]
	v_mfma_f32_16x16x32_bf16 v[108:111], v[128:131], v[192:195], v[108:111]
	v_mfma_f32_16x16x32_bf16 v[100:103], v[136:139], v[192:195], v[100:103]
	v_mfma_f32_16x16x32_bf16 v[88:91], v[128:131], v[200:203], v[88:91]
	v_mfma_f32_16x16x32_bf16 v[80:83], v[136:139], v[200:203], v[80:83]
	v_mfma_f32_16x16x32_bf16 v[124:127], v[132:135], v[180:183], v[124:127]
	v_mfma_f32_16x16x32_bf16 v[120:123], v[140:143], v[180:183], v[120:123]
	v_mfma_f32_16x16x32_bf16 v[116:119], v[132:135], v[188:191], v[116:119]
	v_mfma_f32_16x16x32_bf16 v[112:115], v[140:143], v[188:191], v[112:115]
	v_mfma_f32_16x16x32_bf16 v[108:111], v[132:135], v[196:199], v[108:111]
	v_mfma_f32_16x16x32_bf16 v[100:103], v[140:143], v[196:199], v[100:103]
	v_mfma_f32_16x16x32_bf16 v[88:91], v[132:135], v[204:207], v[88:91]
	v_mfma_f32_16x16x32_bf16 v[80:83], v[140:143], v[204:207], v[80:83]
	s_setprio 0
	s_setprio 1
	v_mfma_f32_16x16x32_bf16 v[104:107], v[144:147], v[176:179], v[104:107]
	v_mfma_f32_16x16x32_bf16 v[96:99], v[168:171], v[176:179], v[96:99]
	v_mfma_f32_16x16x32_bf16 v[92:95], v[144:147], v[184:187], v[92:95]
	v_mfma_f32_16x16x32_bf16 v[84:87], v[168:171], v[184:187], v[84:87]
	v_mfma_f32_16x16x32_bf16 v[76:79], v[144:147], v[192:195], v[76:79]
	v_mfma_f32_16x16x32_bf16 v[72:75], v[168:171], v[192:195], v[72:75]
	v_mfma_f32_16x16x32_bf16 v[68:71], v[144:147], v[200:203], v[68:71]
	v_mfma_f32_16x16x32_bf16 v[64:67], v[168:171], v[200:203], v[64:67]
	v_mfma_f32_16x16x32_bf16 v[104:107], v[148:151], v[180:183], v[104:107]
	v_mfma_f32_16x16x32_bf16 v[96:99], v[172:175], v[180:183], v[96:99]
	v_mfma_f32_16x16x32_bf16 v[92:95], v[148:151], v[188:191], v[92:95]
	v_mfma_f32_16x16x32_bf16 v[84:87], v[172:175], v[188:191], v[84:87]
	v_mfma_f32_16x16x32_bf16 v[76:79], v[148:151], v[196:199], v[76:79]
	v_mfma_f32_16x16x32_bf16 v[72:75], v[172:175], v[196:199], v[72:75]
	v_mfma_f32_16x16x32_bf16 v[68:71], v[148:151], v[204:207], v[68:71]
	v_mfma_f32_16x16x32_bf16 v[64:67], v[172:175], v[204:207], v[64:67]
	s_setprio 0
	s_barrier
	s_add_i32 s68, s79, s33
	v_lshl_add_u64 v[208:209], s[6:7], 0, v[156:157]
	s_mov_b32 m0, s68
	ds_read_b128 v[176:179], v216 offset:16384
	ds_read_b128 v[180:183], v216 offset:17408
	ds_read_b128 v[184:187], v216 offset:18432
	ds_read_b128 v[188:191], v216 offset:19456
	ds_read_b128 v[192:195], v216 offset:20480
	ds_read_b128 v[196:199], v216 offset:21504
	ds_read_b128 v[200:203], v216 offset:22528
	ds_read_b128 v[204:207], v216 offset:23552
	global_load_lds_dwordx4 v[208:209], off
	s_add_i32 m0, s68, 0x2000
	s_add_u32 s84, s6, 0x40000
	v_lshl_add_u64 v[220:221], s[6:7], 0, v[152:153]
	s_addc_u32 s85, s7, 0
	s_add_i32 s68, s80, s33
	global_load_lds_dwordx4 v[220:221], off
	s_mov_b32 m0, s68
	v_lshl_add_u64 v[224:225], s[62:63], 0, v[154:155]
	global_load_lds_dwordx4 v156, s[84:85]
	s_add_i32 m0, s68, 0x2000
	s_nop 0
	global_load_lds_dwordx4 v152, s[84:85]
	v_lshl_add_u64 v[222:223], s[62:63], 0, v[158:159]
	s_mov_b32 m0, s64
	s_nop 0
	global_load_lds_dwordx4 v[222:223], off
	s_mov_b32 m0, s65
	s_nop 0
	global_load_lds_dwordx4 v[224:225], off
	s_waitcnt vmcnt(8)
	s_waitcnt lgkmcnt(0)
	s_barrier
	s_setprio 1
	s_waitcnt lgkmcnt(0)
	v_mfma_f32_16x16x32_bf16 v[60:63], v[128:131], v[176:179], v[60:63]
	v_mfma_f32_16x16x32_bf16 v[56:59], v[136:139], v[176:179], v[56:59]
	v_mfma_f32_16x16x32_bf16 v[52:55], v[128:131], v[184:187], v[52:55]
	v_mfma_f32_16x16x32_bf16 v[48:51], v[136:139], v[184:187], v[48:51]
	v_mfma_f32_16x16x32_bf16 v[40:43], v[128:131], v[192:195], v[40:43]
	v_mfma_f32_16x16x32_bf16 v[32:35], v[136:139], v[192:195], v[32:35]
	v_mfma_f32_16x16x32_bf16 v[20:23], v[128:131], v[200:203], v[20:23]
	v_mfma_f32_16x16x32_bf16 v[16:19], v[136:139], v[200:203], v[16:19]
	v_mfma_f32_16x16x32_bf16 v[60:63], v[132:135], v[180:183], v[60:63]
	v_mfma_f32_16x16x32_bf16 v[56:59], v[140:143], v[180:183], v[56:59]
	v_mfma_f32_16x16x32_bf16 v[52:55], v[132:135], v[188:191], v[52:55]
	v_mfma_f32_16x16x32_bf16 v[48:51], v[140:143], v[188:191], v[48:51]
	v_mfma_f32_16x16x32_bf16 v[40:43], v[132:135], v[196:199], v[40:43]
	v_mfma_f32_16x16x32_bf16 v[32:35], v[140:143], v[196:199], v[32:35]
	v_mfma_f32_16x16x32_bf16 v[20:23], v[132:135], v[204:207], v[20:23]
	v_mfma_f32_16x16x32_bf16 v[16:19], v[140:143], v[204:207], v[16:19]
	s_setprio 0
	s_setprio 1
	v_mfma_f32_16x16x32_bf16 v[44:47], v[144:147], v[176:179], v[44:47]
	v_mfma_f32_16x16x32_bf16 v[36:39], v[168:171], v[176:179], v[36:39]
	v_mfma_f32_16x16x32_bf16 v[28:31], v[144:147], v[184:187], v[28:31]
	v_mfma_f32_16x16x32_bf16 v[24:27], v[168:171], v[184:187], v[24:27]
	v_mfma_f32_16x16x32_bf16 v[12:15], v[144:147], v[192:195], v[12:15]
	v_mfma_f32_16x16x32_bf16 v[8:11], v[168:171], v[192:195], v[8:11]
	v_mfma_f32_16x16x32_bf16 v[4:7], v[144:147], v[200:203], v[4:7]
	v_mfma_f32_16x16x32_bf16 v[0:3], v[168:171], v[200:203], v[0:3]
	v_mfma_f32_16x16x32_bf16 v[44:47], v[148:151], v[180:183], v[44:47]
	v_mfma_f32_16x16x32_bf16 v[36:39], v[172:175], v[180:183], v[36:39]
	v_mfma_f32_16x16x32_bf16 v[28:31], v[148:151], v[188:191], v[28:31]
	v_mfma_f32_16x16x32_bf16 v[24:27], v[172:175], v[188:191], v[24:27]
	v_mfma_f32_16x16x32_bf16 v[12:15], v[148:151], v[196:199], v[12:15]
	v_mfma_f32_16x16x32_bf16 v[8:11], v[172:175], v[196:199], v[8:11]
	v_mfma_f32_16x16x32_bf16 v[4:7], v[148:151], v[204:207], v[4:7]
	v_mfma_f32_16x16x32_bf16 v[0:3], v[172:175], v[204:207], v[0:3]
	s_setprio 0
	s_barrier
	s_add_i32 s68, 0, 0x18000
	s_add_i32 s83, 0, 0x1c000
	v_add_u32_e32 v140, s68, v213
	v_add_u32_e32 v172, s83, v213
	ds_read_b128 v[128:131], v140
	ds_read_b128 v[132:135], v140 offset:1024
	ds_read_b128 v[136:139], v140 offset:2048
	ds_read_b128 v[140:143], v140 offset:3072
	ds_read_b128 v[144:147], v172
	ds_read_b128 v[148:151], v172 offset:1024
	ds_read_b128 v[168:171], v172 offset:2048
	ds_read_b128 v[172:175], v172 offset:3072
	s_add_u32 s62, s62, 0x40000
	s_addc_u32 s63, s63, 0
	s_mov_b32 m0, s66
	ds_read_b128 v[176:179], v216 offset:32768
	ds_read_b128 v[180:183], v216 offset:33792
	ds_read_b128 v[184:187], v216 offset:34816
	ds_read_b128 v[188:191], v216 offset:35840
	ds_read_b128 v[192:195], v216 offset:36864
	ds_read_b128 v[196:199], v216 offset:37888
	ds_read_b128 v[200:203], v216 offset:38912
	ds_read_b128 v[204:207], v216 offset:39936
	global_load_lds_dwordx4 v158, s[62:63]
	s_mov_b32 m0, s67
	s_nop 0
	global_load_lds_dwordx4 v154, s[62:63]
	s_waitcnt vmcnt(8)
	s_waitcnt lgkmcnt(0)
	s_barrier
	s_setprio 1
	s_waitcnt lgkmcnt(0)
	v_mfma_f32_16x16x32_bf16 v[124:127], v[128:131], v[176:179], v[124:127]
	v_mfma_f32_16x16x32_bf16 v[120:123], v[136:139], v[176:179], v[120:123]
	v_mfma_f32_16x16x32_bf16 v[116:119], v[128:131], v[184:187], v[116:119]
	v_mfma_f32_16x16x32_bf16 v[112:115], v[136:139], v[184:187], v[112:115]
	v_mfma_f32_16x16x32_bf16 v[108:111], v[128:131], v[192:195], v[108:111]
	v_mfma_f32_16x16x32_bf16 v[100:103], v[136:139], v[192:195], v[100:103]
	v_mfma_f32_16x16x32_bf16 v[88:91], v[128:131], v[200:203], v[88:91]
	v_mfma_f32_16x16x32_bf16 v[80:83], v[136:139], v[200:203], v[80:83]
	v_mfma_f32_16x16x32_bf16 v[124:127], v[132:135], v[180:183], v[124:127]
	v_mfma_f32_16x16x32_bf16 v[120:123], v[140:143], v[180:183], v[120:123]
	v_mfma_f32_16x16x32_bf16 v[116:119], v[132:135], v[188:191], v[116:119]
	v_mfma_f32_16x16x32_bf16 v[112:115], v[140:143], v[188:191], v[112:115]
	v_mfma_f32_16x16x32_bf16 v[108:111], v[132:135], v[196:199], v[108:111]
	v_mfma_f32_16x16x32_bf16 v[100:103], v[140:143], v[196:199], v[100:103]
	v_mfma_f32_16x16x32_bf16 v[88:91], v[132:135], v[204:207], v[88:91]
	v_mfma_f32_16x16x32_bf16 v[80:83], v[140:143], v[204:207], v[80:83]
	s_setprio 0
	s_setprio 1
	v_mfma_f32_16x16x32_bf16 v[104:107], v[144:147], v[176:179], v[104:107]
	v_mfma_f32_16x16x32_bf16 v[96:99], v[168:171], v[176:179], v[96:99]
	v_mfma_f32_16x16x32_bf16 v[92:95], v[144:147], v[184:187], v[92:95]
	v_mfma_f32_16x16x32_bf16 v[84:87], v[168:171], v[184:187], v[84:87]
	v_mfma_f32_16x16x32_bf16 v[76:79], v[144:147], v[192:195], v[76:79]
	v_mfma_f32_16x16x32_bf16 v[72:75], v[168:171], v[192:195], v[72:75]
	v_mfma_f32_16x16x32_bf16 v[68:71], v[144:147], v[200:203], v[68:71]
	v_mfma_f32_16x16x32_bf16 v[64:67], v[168:171], v[200:203], v[64:67]
	v_mfma_f32_16x16x32_bf16 v[104:107], v[148:151], v[180:183], v[104:107]
	v_mfma_f32_16x16x32_bf16 v[96:99], v[172:175], v[180:183], v[96:99]
	v_mfma_f32_16x16x32_bf16 v[92:95], v[148:151], v[188:191], v[92:95]
	v_mfma_f32_16x16x32_bf16 v[84:87], v[172:175], v[188:191], v[84:87]
	v_mfma_f32_16x16x32_bf16 v[76:79], v[148:151], v[196:199], v[76:79]
	v_mfma_f32_16x16x32_bf16 v[72:75], v[172:175], v[196:199], v[72:75]
	v_mfma_f32_16x16x32_bf16 v[68:71], v[148:151], v[204:207], v[68:71]
	v_mfma_f32_16x16x32_bf16 v[64:67], v[172:175], v[204:207], v[64:67]
	s_setprio 0
	s_barrier
	s_add_i32 s62, s68, s33
	v_lshl_add_u64 v[208:209], v[208:209], 0, s[42:43]
	s_mov_b32 m0, s62
	ds_read_b128 v[176:179], v216 offset:49152
	ds_read_b128 v[180:183], v216 offset:50176
	ds_read_b128 v[184:187], v216 offset:51200
	ds_read_b128 v[188:191], v216 offset:52224
	ds_read_b128 v[192:195], v216 offset:53248
	ds_read_b128 v[196:199], v216 offset:54272
	ds_read_b128 v[200:203], v216 offset:55296
	ds_read_b128 v[204:207], v216 offset:56320
	global_load_lds_dwordx4 v[208:209], off
	s_add_i32 m0, s62, 0x2000
	s_add_u32 s6, s6, 0x40080
	v_lshl_add_u64 v[208:209], v[220:221], 0, s[42:43]
	s_addc_u32 s7, s7, 0
	s_add_i32 s62, s83, s33
	global_load_lds_dwordx4 v[208:209], off
	s_mov_b32 m0, s62
	s_nop 0
	global_load_lds_dwordx4 v156, s[6:7]
	s_add_i32 m0, s62, 0x2000
	s_nop 0
	global_load_lds_dwordx4 v152, s[6:7]
	v_lshl_add_u64 v[208:209], v[222:223], 0, s[42:43]
	s_mov_b32 m0, s75
	s_nop 0
	global_load_lds_dwordx4 v[208:209], off
	v_lshl_add_u64 v[208:209], v[224:225], 0, s[42:43]
	s_mov_b32 m0, s76
	s_nop 0
	global_load_lds_dwordx4 v[208:209], off
	s_waitcnt vmcnt(8)
	s_waitcnt lgkmcnt(0)
	s_barrier
	s_setprio 1
	s_waitcnt lgkmcnt(0)
	v_mfma_f32_16x16x32_bf16 v[60:63], v[128:131], v[176:179], v[60:63]
	v_mfma_f32_16x16x32_bf16 v[56:59], v[136:139], v[176:179], v[56:59]
	v_mfma_f32_16x16x32_bf16 v[52:55], v[128:131], v[184:187], v[52:55]
	v_mfma_f32_16x16x32_bf16 v[48:51], v[136:139], v[184:187], v[48:51]
	v_mfma_f32_16x16x32_bf16 v[40:43], v[128:131], v[192:195], v[40:43]
	v_mfma_f32_16x16x32_bf16 v[32:35], v[136:139], v[192:195], v[32:35]
	v_mfma_f32_16x16x32_bf16 v[20:23], v[128:131], v[200:203], v[20:23]
	v_mfma_f32_16x16x32_bf16 v[16:19], v[136:139], v[200:203], v[16:19]
	v_mfma_f32_16x16x32_bf16 v[60:63], v[132:135], v[180:183], v[60:63]
	v_mfma_f32_16x16x32_bf16 v[56:59], v[140:143], v[180:183], v[56:59]
	v_mfma_f32_16x16x32_bf16 v[52:55], v[132:135], v[188:191], v[52:55]
	v_mfma_f32_16x16x32_bf16 v[48:51], v[140:143], v[188:191], v[48:51]
	v_mfma_f32_16x16x32_bf16 v[40:43], v[132:135], v[196:199], v[40:43]
	v_mfma_f32_16x16x32_bf16 v[32:35], v[140:143], v[196:199], v[32:35]
	v_mfma_f32_16x16x32_bf16 v[20:23], v[132:135], v[204:207], v[20:23]
	v_mfma_f32_16x16x32_bf16 v[16:19], v[140:143], v[204:207], v[16:19]
	s_setprio 0
	s_setprio 1
	v_mfma_f32_16x16x32_bf16 v[44:47], v[144:147], v[176:179], v[44:47]
	v_mfma_f32_16x16x32_bf16 v[36:39], v[168:171], v[176:179], v[36:39]
	v_mfma_f32_16x16x32_bf16 v[28:31], v[144:147], v[184:187], v[28:31]
	v_mfma_f32_16x16x32_bf16 v[24:27], v[168:171], v[184:187], v[24:27]
	v_mfma_f32_16x16x32_bf16 v[12:15], v[144:147], v[192:195], v[12:15]
	v_mfma_f32_16x16x32_bf16 v[8:11], v[168:171], v[192:195], v[8:11]
	v_mfma_f32_16x16x32_bf16 v[4:7], v[144:147], v[200:203], v[4:7]
	v_mfma_f32_16x16x32_bf16 v[0:3], v[168:171], v[200:203], v[0:3]
	v_mfma_f32_16x16x32_bf16 v[44:47], v[148:151], v[180:183], v[44:47]
	v_mfma_f32_16x16x32_bf16 v[36:39], v[172:175], v[180:183], v[36:39]
	v_mfma_f32_16x16x32_bf16 v[28:31], v[148:151], v[188:191], v[28:31]
	v_mfma_f32_16x16x32_bf16 v[24:27], v[172:175], v[188:191], v[24:27]
	v_mfma_f32_16x16x32_bf16 v[12:15], v[148:151], v[196:199], v[12:15]
	v_mfma_f32_16x16x32_bf16 v[8:11], v[172:175], v[196:199], v[8:11]
	v_mfma_f32_16x16x32_bf16 v[4:7], v[148:151], v[204:207], v[4:7]
	v_mfma_f32_16x16x32_bf16 v[0:3], v[172:175], v[204:207], v[0:3]
	s_setprio 0
	s_barrier
	s_add_i32 s57, s57, 2
	s_add_u32 s4, s4, 0x100
	s_addc_u32 s5, s5, 0
	s_add_u32 s28, s28, 0x100
	s_addc_u32 s55, s55, 0
	s_cmp_gt_u32 s57, 13
	s_cbranch_scc0 .LBB0_704
	s_and_b64 vcc, exec, s[44:45]
	s_cbranch_vccz .LBB0_707
	s_barrier

.LBB0_862:
	ds_read_b128 v[152:155], v159
	ds_read_b128 v[164:167], v159 offset:1024
	ds_read_b128 v[168:171], v159 offset:2048
	ds_read_b128 v[172:175], v159 offset:3072
	ds_read_b128 v[176:179], v160
	ds_read_b128 v[180:183], v160 offset:1024
	ds_read_b128 v[184:187], v160 offset:2048
	ds_read_b128 v[188:191], v160 offset:3072
	s_add_u32 s4, s40, 0x100
	s_addc_u32 s5, s41, 0
	s_cmp_eq_u32 s58, 2
	s_cselect_b32 s45, s35, s5
	s_cselect_b32 s44, s34, s4
	s_cselect_b32 s43, s37, s57
	s_cselect_b32 s42, s36, s56
	s_add_i32 m0, s11, 0xc000
	ds_read_b128 v[192:195], v161
	ds_read_b128 v[196:199], v161 offset:1024
	ds_read_b128 v[200:203], v161 offset:2048
	ds_read_b128 v[204:207], v161 offset:3072
	ds_read_b128 v[212:215], v161 offset:4096
	ds_read_b128 v[216:219], v161 offset:5120
	ds_read_b128 v[220:223], v161 offset:6144
	ds_read_b128 v[224:227], v161 offset:7168
	global_load_lds_dwordx4 v144, s[40:41]
	s_add_i32 m0, s11, 0xe000
	s_nop 0
	global_load_lds_dwordx4 v146, s[40:41]
	s_waitcnt vmcnt(8)
	s_waitcnt lgkmcnt(0)
	s_barrier
	s_setprio 1
	s_waitcnt lgkmcnt(0)
	v_mfma_f32_16x16x32_bf16 v[124:127], v[152:155], v[192:195], v[124:127]
	v_mfma_f32_16x16x32_bf16 v[120:123], v[168:171], v[192:195], v[120:123]
	v_mfma_f32_16x16x32_bf16 v[108:111], v[152:155], v[200:203], v[108:111]
	v_mfma_f32_16x16x32_bf16 v[104:107], v[168:171], v[200:203], v[104:107]
	v_mfma_f32_16x16x32_bf16 v[92:95], v[152:155], v[212:215], v[92:95]
	v_mfma_f32_16x16x32_bf16 v[88:91], v[168:171], v[212:215], v[88:91]
	v_mfma_f32_16x16x32_bf16 v[76:79], v[152:155], v[220:223], v[76:79]
	v_mfma_f32_16x16x32_bf16 v[72:75], v[168:171], v[220:223], v[72:75]
	v_mfma_f32_16x16x32_bf16 v[124:127], v[164:167], v[196:199], v[124:127]
	v_mfma_f32_16x16x32_bf16 v[120:123], v[172:175], v[196:199], v[120:123]
	v_mfma_f32_16x16x32_bf16 v[108:111], v[164:167], v[204:207], v[108:111]
	v_mfma_f32_16x16x32_bf16 v[104:107], v[172:175], v[204:207], v[104:107]
	v_mfma_f32_16x16x32_bf16 v[92:95], v[164:167], v[216:219], v[92:95]
	v_mfma_f32_16x16x32_bf16 v[88:91], v[172:175], v[216:219], v[88:91]
	v_mfma_f32_16x16x32_bf16 v[76:79], v[164:167], v[224:227], v[76:79]
	v_mfma_f32_16x16x32_bf16 v[72:75], v[172:175], v[224:227], v[72:75]
	s_setprio 0
	s_setprio 1
	v_mfma_f32_16x16x32_bf16 v[116:119], v[176:179], v[192:195], v[116:119]
	v_mfma_f32_16x16x32_bf16 v[112:115], v[184:187], v[192:195], v[112:115]
	v_mfma_f32_16x16x32_bf16 v[100:103], v[176:179], v[200:203], v[100:103]
	v_mfma_f32_16x16x32_bf16 v[96:99], v[184:187], v[200:203], v[96:99]
	v_mfma_f32_16x16x32_bf16 v[84:87], v[176:179], v[212:215], v[84:87]
	v_mfma_f32_16x16x32_bf16 v[80:83], v[184:187], v[212:215], v[80:83]
	v_mfma_f32_16x16x32_bf16 v[68:71], v[176:179], v[220:223], v[68:71]
	v_mfma_f32_16x16x32_bf16 v[64:67], v[184:187], v[220:223], v[64:67]
	v_mfma_f32_16x16x32_bf16 v[116:119], v[180:183], v[196:199], v[116:119]
	v_mfma_f32_16x16x32_bf16 v[112:115], v[188:191], v[196:199], v[112:115]
	v_mfma_f32_16x16x32_bf16 v[100:103], v[180:183], v[204:207], v[100:103]
	v_mfma_f32_16x16x32_bf16 v[96:99], v[188:191], v[204:207], v[96:99]
	v_mfma_f32_16x16x32_bf16 v[84:87], v[180:183], v[216:219], v[84:87]
	v_mfma_f32_16x16x32_bf16 v[80:83], v[188:191], v[216:219], v[80:83]
	v_mfma_f32_16x16x32_bf16 v[68:71], v[180:183], v[224:227], v[68:71]
	v_mfma_f32_16x16x32_bf16 v[64:67], v[188:191], v[224:227], v[64:67]
	s_setprio 0
	s_barrier
	s_add_i32 s40, s48, s10
	v_lshl_add_u64 v[156:157], s[42:43], 0, v[130:131]
	s_mov_b32 m0, s40
	ds_read_b128 v[192:195], v161 offset:16384
	ds_read_b128 v[196:199], v161 offset:17408
	ds_read_b128 v[200:203], v161 offset:18432
	ds_read_b128 v[204:207], v161 offset:19456
	ds_read_b128 v[212:215], v161 offset:20480
	ds_read_b128 v[216:219], v161 offset:21504
	ds_read_b128 v[220:223], v161 offset:22528
	ds_read_b128 v[224:227], v161 offset:23552
	global_load_lds_dwordx4 v[156:157], off
	s_add_i32 m0, s40, 0x2000
	s_add_u32 s40, s42, 0x18000
	v_lshl_add_u64 v[208:209], s[42:43], 0, v[134:135]
	s_addc_u32 s41, s43, 0
	s_add_i32 s59, s49, s10
	global_load_lds_dwordx4 v[208:209], off
	s_mov_b32 m0, s59
	v_lshl_add_u64 v[230:231], s[44:45], 0, v[132:133]
	global_load_lds_dwordx4 v130, s[40:41]
	s_add_i32 m0, s59, 0x2000
	s_nop 0
	global_load_lds_dwordx4 v134, s[40:41]
	v_lshl_add_u64 v[228:229], s[44:45], 0, v[128:129]
	s_mov_b32 m0, s11
	s_nop 0
	global_load_lds_dwordx4 v[228:229], off
	s_mov_b32 m0, s14
	s_nop 0
	global_load_lds_dwordx4 v[230:231], off
	s_waitcnt vmcnt(8)
	s_waitcnt lgkmcnt(0)
	s_barrier
	s_setprio 1
	s_waitcnt lgkmcnt(0)
	v_mfma_f32_16x16x32_bf16 v[60:63], v[152:155], v[192:195], v[60:63]
	v_mfma_f32_16x16x32_bf16 v[56:59], v[168:171], v[192:195], v[56:59]
	v_mfma_f32_16x16x32_bf16 v[44:47], v[152:155], v[200:203], v[44:47]
	v_mfma_f32_16x16x32_bf16 v[40:43], v[168:171], v[200:203], v[40:43]
	v_mfma_f32_16x16x32_bf16 v[28:31], v[152:155], v[212:215], v[28:31]
	v_mfma_f32_16x16x32_bf16 v[24:27], v[168:171], v[212:215], v[24:27]
	v_mfma_f32_16x16x32_bf16 v[12:15], v[152:155], v[220:223], v[12:15]
	v_mfma_f32_16x16x32_bf16 v[8:11], v[168:171], v[220:223], v[8:11]
	v_mfma_f32_16x16x32_bf16 v[60:63], v[164:167], v[196:199], v[60:63]
	v_mfma_f32_16x16x32_bf16 v[56:59], v[172:175], v[196:199], v[56:59]
	v_mfma_f32_16x16x32_bf16 v[44:47], v[164:167], v[204:207], v[44:47]
	v_mfma_f32_16x16x32_bf16 v[40:43], v[172:175], v[204:207], v[40:43]
	v_mfma_f32_16x16x32_bf16 v[28:31], v[164:167], v[216:219], v[28:31]
	v_mfma_f32_16x16x32_bf16 v[24:27], v[172:175], v[216:219], v[24:27]
	v_mfma_f32_16x16x32_bf16 v[12:15], v[164:167], v[224:227], v[12:15]
	v_mfma_f32_16x16x32_bf16 v[8:11], v[172:175], v[224:227], v[8:11]
	s_setprio 0
	s_setprio 1
	v_mfma_f32_16x16x32_bf16 v[52:55], v[176:179], v[192:195], v[52:55]
	v_mfma_f32_16x16x32_bf16 v[48:51], v[184:187], v[192:195], v[48:51]
	v_mfma_f32_16x16x32_bf16 v[36:39], v[176:179], v[200:203], v[36:39]
	v_mfma_f32_16x16x32_bf16 v[32:35], v[184:187], v[200:203], v[32:35]
	v_mfma_f32_16x16x32_bf16 v[20:23], v[176:179], v[212:215], v[20:23]
	v_mfma_f32_16x16x32_bf16 v[16:19], v[184:187], v[212:215], v[16:19]
	v_mfma_f32_16x16x32_bf16 v[4:7], v[176:179], v[220:223], v[4:7]
	v_mfma_f32_16x16x32_bf16 v[0:3], v[184:187], v[220:223], v[0:3]
	v_mfma_f32_16x16x32_bf16 v[52:55], v[180:183], v[196:199], v[52:55]
	v_mfma_f32_16x16x32_bf16 v[48:51], v[188:191], v[196:199], v[48:51]
	v_mfma_f32_16x16x32_bf16 v[36:39], v[180:183], v[204:207], v[36:39]
	v_mfma_f32_16x16x32_bf16 v[32:35], v[188:191], v[204:207], v[32:35]
	v_mfma_f32_16x16x32_bf16 v[20:23], v[180:183], v[216:219], v[20:23]
	v_mfma_f32_16x16x32_bf16 v[16:19], v[188:191], v[216:219], v[16:19]
	v_mfma_f32_16x16x32_bf16 v[4:7], v[180:183], v[224:227], v[4:7]
	v_mfma_f32_16x16x32_bf16 v[0:3], v[188:191], v[224:227], v[0:3]
	s_setprio 0
	s_barrier
	s_add_i32 s59, 0, 0x18000
	v_add_u32_e32 v163, s59, v158
	s_add_i32 s60, 0, 0x1c000
	ds_read_b128 v[152:155], v163
	ds_read_b128 v[164:167], v163 offset:1024
	ds_read_b128 v[168:171], v163 offset:2048
	ds_read_b128 v[172:175], v163 offset:3072
	v_add_u32_e32 v163, s60, v158
	ds_read_b128 v[176:179], v163
	ds_read_b128 v[180:183], v163 offset:1024
	ds_read_b128 v[184:187], v163 offset:2048
	ds_read_b128 v[188:191], v163 offset:3072
	s_add_u32 s40, s44, 0x18000
	s_addc_u32 s41, s45, 0
	s_mov_b32 m0, s15
	ds_read_b128 v[192:195], v161 offset:32768
	ds_read_b128 v[196:199], v161 offset:33792
	ds_read_b128 v[200:203], v161 offset:34816
	ds_read_b128 v[204:207], v161 offset:35840
	ds_read_b128 v[212:215], v161 offset:36864
	ds_read_b128 v[216:219], v161 offset:37888
	ds_read_b128 v[220:223], v161 offset:38912
	ds_read_b128 v[224:227], v161 offset:39936
	global_load_lds_dwordx4 v128, s[40:41]
	s_mov_b32 m0, s28
	s_nop 0
	global_load_lds_dwordx4 v132, s[40:41]
	s_waitcnt vmcnt(8)
	s_waitcnt lgkmcnt(0)
	s_barrier
	s_setprio 1
	s_waitcnt lgkmcnt(0)
	v_mfma_f32_16x16x32_bf16 v[124:127], v[152:155], v[192:195], v[124:127]
	v_mfma_f32_16x16x32_bf16 v[120:123], v[168:171], v[192:195], v[120:123]
	v_mfma_f32_16x16x32_bf16 v[108:111], v[152:155], v[200:203], v[108:111]
	v_mfma_f32_16x16x32_bf16 v[104:107], v[168:171], v[200:203], v[104:107]
	v_mfma_f32_16x16x32_bf16 v[92:95], v[152:155], v[212:215], v[92:95]
	v_mfma_f32_16x16x32_bf16 v[88:91], v[168:171], v[212:215], v[88:91]
	v_mfma_f32_16x16x32_bf16 v[76:79], v[152:155], v[220:223], v[76:79]
	v_mfma_f32_16x16x32_bf16 v[72:75], v[168:171], v[220:223], v[72:75]
	v_mfma_f32_16x16x32_bf16 v[124:127], v[164:167], v[196:199], v[124:127]
	v_mfma_f32_16x16x32_bf16 v[120:123], v[172:175], v[196:199], v[120:123]
	v_mfma_f32_16x16x32_bf16 v[108:111], v[164:167], v[204:207], v[108:111]
	v_mfma_f32_16x16x32_bf16 v[104:107], v[172:175], v[204:207], v[104:107]
	v_mfma_f32_16x16x32_bf16 v[92:95], v[164:167], v[216:219], v[92:95]
	v_mfma_f32_16x16x32_bf16 v[88:91], v[172:175], v[216:219], v[88:91]
	v_mfma_f32_16x16x32_bf16 v[76:79], v[164:167], v[224:227], v[76:79]
	v_mfma_f32_16x16x32_bf16 v[72:75], v[172:175], v[224:227], v[72:75]
	s_setprio 0
	s_setprio 1
	v_mfma_f32_16x16x32_bf16 v[116:119], v[176:179], v[192:195], v[116:119]
	v_mfma_f32_16x16x32_bf16 v[112:115], v[184:187], v[192:195], v[112:115]
	v_mfma_f32_16x16x32_bf16 v[100:103], v[176:179], v[200:203], v[100:103]
	v_mfma_f32_16x16x32_bf16 v[96:99], v[184:187], v[200:203], v[96:99]
	v_mfma_f32_16x16x32_bf16 v[84:87], v[176:179], v[212:215], v[84:87]
	v_mfma_f32_16x16x32_bf16 v[80:83], v[184:187], v[212:215], v[80:83]
	v_mfma_f32_16x16x32_bf16 v[68:71], v[176:179], v[220:223], v[68:71]
	v_mfma_f32_16x16x32_bf16 v[64:67], v[184:187], v[220:223], v[64:67]
	v_mfma_f32_16x16x32_bf16 v[116:119], v[180:183], v[196:199], v[116:119]
	v_mfma_f32_16x16x32_bf16 v[112:115], v[188:191], v[196:199], v[112:115]
	v_mfma_f32_16x16x32_bf16 v[100:103], v[180:183], v[204:207], v[100:103]
	v_mfma_f32_16x16x32_bf16 v[96:99], v[188:191], v[204:207], v[96:99]
	v_mfma_f32_16x16x32_bf16 v[84:87], v[180:183], v[216:219], v[84:87]
	v_mfma_f32_16x16x32_bf16 v[80:83], v[188:191], v[216:219], v[80:83]
	v_mfma_f32_16x16x32_bf16 v[68:71], v[180:183], v[224:227], v[68:71]
	v_mfma_f32_16x16x32_bf16 v[64:67], v[188:191], v[224:227], v[64:67]
	s_setprio 0
	s_barrier
	s_add_i32 s40, s59, s10
	v_lshl_add_u64 v[156:157], v[156:157], 0, s[8:9]
	s_mov_b32 m0, s40
	ds_read_b128 v[192:195], v161 offset:49152
	ds_read_b128 v[196:199], v161 offset:50176
	ds_read_b128 v[200:203], v161 offset:51200
	ds_read_b128 v[204:207], v161 offset:52224
	ds_read_b128 v[212:215], v161 offset:53248
	ds_read_b128 v[216:219], v161 offset:54272
	ds_read_b128 v[220:223], v161 offset:55296
	ds_read_b128 v[224:227], v161 offset:56320
	global_load_lds_dwordx4 v[156:157], off
	s_add_i32 m0, s40, 0x2000
	s_add_u32 s40, s42, 0x18080
	v_lshl_add_u64 v[156:157], v[208:209], 0, s[8:9]
	s_addc_u32 s41, s43, 0
	s_add_i32 s42, s60, s10
	global_load_lds_dwordx4 v[156:157], off
	s_mov_b32 m0, s42
	s_nop 0
	global_load_lds_dwordx4 v130, s[40:41]
	s_add_i32 m0, s42, 0x2000
	s_nop 0
	global_load_lds_dwordx4 v134, s[40:41]
	v_lshl_add_u64 v[156:157], v[228:229], 0, s[8:9]
	s_mov_b32 m0, s33
	s_nop 0
	global_load_lds_dwordx4 v[156:157], off
	v_lshl_add_u64 v[156:157], v[230:231], 0, s[8:9]
	s_mov_b32 m0, s46
	s_nop 0
	global_load_lds_dwordx4 v[156:157], off
	s_waitcnt vmcnt(8)
	s_waitcnt lgkmcnt(0)
	s_barrier
	s_setprio 1
	s_waitcnt lgkmcnt(0)
	v_mfma_f32_16x16x32_bf16 v[60:63], v[152:155], v[192:195], v[60:63]
	v_mfma_f32_16x16x32_bf16 v[56:59], v[168:171], v[192:195], v[56:59]
	v_mfma_f32_16x16x32_bf16 v[44:47], v[152:155], v[200:203], v[44:47]
	v_mfma_f32_16x16x32_bf16 v[40:43], v[168:171], v[200:203], v[40:43]
	v_mfma_f32_16x16x32_bf16 v[28:31], v[152:155], v[212:215], v[28:31]
	v_mfma_f32_16x16x32_bf16 v[24:27], v[168:171], v[212:215], v[24:27]
	v_mfma_f32_16x16x32_bf16 v[12:15], v[152:155], v[220:223], v[12:15]
	v_mfma_f32_16x16x32_bf16 v[8:11], v[168:171], v[220:223], v[8:11]
	v_mfma_f32_16x16x32_bf16 v[60:63], v[164:167], v[196:199], v[60:63]
	v_mfma_f32_16x16x32_bf16 v[56:59], v[172:175], v[196:199], v[56:59]
	v_mfma_f32_16x16x32_bf16 v[44:47], v[164:167], v[204:207], v[44:47]
	v_mfma_f32_16x16x32_bf16 v[40:43], v[172:175], v[204:207], v[40:43]
	v_mfma_f32_16x16x32_bf16 v[28:31], v[164:167], v[216:219], v[28:31]
	v_mfma_f32_16x16x32_bf16 v[24:27], v[172:175], v[216:219], v[24:27]
	v_mfma_f32_16x16x32_bf16 v[12:15], v[164:167], v[224:227], v[12:15]
	v_mfma_f32_16x16x32_bf16 v[8:11], v[172:175], v[224:227], v[8:11]
	s_setprio 0
	s_setprio 1
	v_mfma_f32_16x16x32_bf16 v[52:55], v[176:179], v[192:195], v[52:55]
	v_mfma_f32_16x16x32_bf16 v[48:51], v[184:187], v[192:195], v[48:51]
	v_mfma_f32_16x16x32_bf16 v[36:39], v[176:179], v[200:203], v[36:39]
	v_mfma_f32_16x16x32_bf16 v[32:35], v[184:187], v[200:203], v[32:35]
	v_mfma_f32_16x16x32_bf16 v[20:23], v[176:179], v[212:215], v[20:23]
	v_mfma_f32_16x16x32_bf16 v[16:19], v[184:187], v[212:215], v[16:19]
	v_mfma_f32_16x16x32_bf16 v[4:7], v[176:179], v[220:223], v[4:7]
	v_mfma_f32_16x16x32_bf16 v[0:3], v[184:187], v[220:223], v[0:3]
	v_mfma_f32_16x16x32_bf16 v[52:55], v[180:183], v[196:199], v[52:55]
	v_mfma_f32_16x16x32_bf16 v[48:51], v[188:191], v[196:199], v[48:51]
	v_mfma_f32_16x16x32_bf16 v[36:39], v[180:183], v[204:207], v[36:39]
	v_mfma_f32_16x16x32_bf16 v[32:35], v[188:191], v[204:207], v[32:35]
	v_mfma_f32_16x16x32_bf16 v[20:23], v[180:183], v[216:219], v[20:23]
	v_mfma_f32_16x16x32_bf16 v[16:19], v[188:191], v[216:219], v[16:19]
	v_mfma_f32_16x16x32_bf16 v[4:7], v[180:183], v[224:227], v[4:7]
	v_mfma_f32_16x16x32_bf16 v[0:3], v[188:191], v[224:227], v[0:3]
	s_setprio 0
	s_barrier
	s_add_i32 s58, s58, 2
	s_add_u32 s56, s56, 0x100
	s_addc_u32 s57, s57, 0
	s_cmp_gt_u32 s58, 3
	s_mov_b64 s[40:41], s[4:5]
	s_cbranch_scc0 .LBB0_862
	s_and_b64 vcc, exec, s[20:21]
	s_cbranch_vccz .LBB0_865
	s_barrier

.LBB0_894:
	s_add_u32 s46, s34, s40
	s_addc_u32 s47, s35, s41
	s_add_u32 s44, s46, 0x100
	s_addc_u32 s45, s47, 0
	s_and_b64 s[42:43], s[38:39], exec
	s_cselect_b32 s43, s19, s45
	s_cselect_b32 s42, s53, s44
	s_add_u32 s40, s30, s40
	s_addc_u32 s41, s31, s41
	s_add_u32 s40, s40, 0x100
	s_addc_u32 s41, s41, 0
	s_and_b64 s[38:39], s[38:39], exec
	s_cselect_b32 s45, s9, s41
	s_cselect_b32 s44, s54, s40
	s_add_u32 s48, s46, 0x10080
	ds_read_b128 v[144:147], v150
	ds_read_b128 v[154:157], v150 offset:1024
	ds_read_b128 v[158:161], v150 offset:2048
	ds_read_b128 v[162:165], v150 offset:3072
	ds_read_b128 v[166:169], v151
	ds_read_b128 v[170:173], v151 offset:1024
	ds_read_b128 v[174:177], v151 offset:2048
	ds_read_b128 v[178:181], v151 offset:3072
	s_addc_u32 s49, s47, 0
	s_add_i32 s64, s50, s10
	s_add_i32 m0, s11, 0xc000
	s_add_i32 s65, s11, 0xe000
	s_add_i32 s61, s64, 0x2000
	s_add_u32 s46, s44, 0x10000
	s_addc_u32 s47, s45, 0
	s_add_i32 s63, s51, s10
	s_add_i32 s62, s63, 0x2000
	s_add_i32 s60, 0, 0x18000
	s_add_i32 s59, 0, 0x1c000
	s_add_u32 s40, s42, 0x10000
	s_addc_u32 s41, s43, 0
	s_add_i32 s58, s60, s10
	s_add_i32 s56, s58, 0x2000
	s_add_u32 s38, s44, 0x10080
	s_addc_u32 s39, s45, 0
	s_add_i32 s57, s59, s10
	s_add_i32 s55, s57, 0x2000
	ds_read_b128 v[182:185], v152
	ds_read_b128 v[186:189], v152 offset:1024
	ds_read_b128 v[190:193], v152 offset:2048
	ds_read_b128 v[194:197], v152 offset:3072
	ds_read_b128 v[198:201], v152 offset:4096
	ds_read_b128 v[202:205], v152 offset:5120
	ds_read_b128 v[206:209], v152 offset:6144
	ds_read_b128 v[212:215], v152 offset:7168
	global_load_lds_dwordx4 v134, s[48:49]
	s_mov_b32 m0, s65
	s_nop 0
	global_load_lds_dwordx4 v130, s[48:49]
	s_waitcnt vmcnt(8)
	s_waitcnt lgkmcnt(0)
	s_barrier
	s_setprio 1
	s_waitcnt lgkmcnt(0)
	v_mfma_f32_16x16x32_bf16 v[124:127], v[144:147], v[182:185], v[124:127]
	v_mfma_f32_16x16x32_bf16 v[120:123], v[158:161], v[182:185], v[120:123]
	v_mfma_f32_16x16x32_bf16 v[108:111], v[144:147], v[190:193], v[108:111]
	v_mfma_f32_16x16x32_bf16 v[104:107], v[158:161], v[190:193], v[104:107]
	v_mfma_f32_16x16x32_bf16 v[92:95], v[144:147], v[198:201], v[92:95]
	v_mfma_f32_16x16x32_bf16 v[88:91], v[158:161], v[198:201], v[88:91]
	v_mfma_f32_16x16x32_bf16 v[76:79], v[144:147], v[206:209], v[76:79]
	v_mfma_f32_16x16x32_bf16 v[72:75], v[158:161], v[206:209], v[72:75]
	v_mfma_f32_16x16x32_bf16 v[124:127], v[154:157], v[186:189], v[124:127]
	v_mfma_f32_16x16x32_bf16 v[120:123], v[162:165], v[186:189], v[120:123]
	v_mfma_f32_16x16x32_bf16 v[108:111], v[154:157], v[194:197], v[108:111]
	v_mfma_f32_16x16x32_bf16 v[104:107], v[162:165], v[194:197], v[104:107]
	v_mfma_f32_16x16x32_bf16 v[92:95], v[154:157], v[202:205], v[92:95]
	v_mfma_f32_16x16x32_bf16 v[88:91], v[162:165], v[202:205], v[88:91]
	v_mfma_f32_16x16x32_bf16 v[76:79], v[154:157], v[212:215], v[76:79]
	v_mfma_f32_16x16x32_bf16 v[72:75], v[162:165], v[212:215], v[72:75]
	s_setprio 0
	s_setprio 1
	v_mfma_f32_16x16x32_bf16 v[116:119], v[166:169], v[182:185], v[116:119]
	v_mfma_f32_16x16x32_bf16 v[112:115], v[174:177], v[182:185], v[112:115]
	v_mfma_f32_16x16x32_bf16 v[100:103], v[166:169], v[190:193], v[100:103]
	v_mfma_f32_16x16x32_bf16 v[96:99], v[174:177], v[190:193], v[96:99]
	v_mfma_f32_16x16x32_bf16 v[84:87], v[166:169], v[198:201], v[84:87]
	v_mfma_f32_16x16x32_bf16 v[80:83], v[174:177], v[198:201], v[80:83]
	v_mfma_f32_16x16x32_bf16 v[68:71], v[166:169], v[206:209], v[68:71]
	v_mfma_f32_16x16x32_bf16 v[64:67], v[174:177], v[206:209], v[64:67]
	v_mfma_f32_16x16x32_bf16 v[116:119], v[170:173], v[186:189], v[116:119]
	v_mfma_f32_16x16x32_bf16 v[112:115], v[178:181], v[186:189], v[112:115]
	v_mfma_f32_16x16x32_bf16 v[100:103], v[170:173], v[194:197], v[100:103]
	v_mfma_f32_16x16x32_bf16 v[96:99], v[178:181], v[194:197], v[96:99]
	v_mfma_f32_16x16x32_bf16 v[84:87], v[170:173], v[202:205], v[84:87]
	v_mfma_f32_16x16x32_bf16 v[80:83], v[178:181], v[202:205], v[80:83]
	v_mfma_f32_16x16x32_bf16 v[68:71], v[170:173], v[212:215], v[68:71]
	v_mfma_f32_16x16x32_bf16 v[64:67], v[178:181], v[212:215], v[64:67]
	s_setprio 0
	s_barrier
	s_mov_b32 m0, s64
	v_lshl_add_u64 v[216:217], s[44:45], 0, v[132:133]
	ds_read_b128 v[182:185], v152 offset:16384
	ds_read_b128 v[186:189], v152 offset:17408
	ds_read_b128 v[190:193], v152 offset:18432
	ds_read_b128 v[194:197], v152 offset:19456
	ds_read_b128 v[198:201], v152 offset:20480
	ds_read_b128 v[202:205], v152 offset:21504
	ds_read_b128 v[206:209], v152 offset:22528
	ds_read_b128 v[212:215], v152 offset:23552
	global_load_lds_dwordx4 v[216:217], off
	v_lshl_add_u64 v[218:219], s[44:45], 0, v[128:129]
	s_mov_b32 m0, s61
	s_nop 0
	global_load_lds_dwordx4 v[218:219], off
	s_mov_b32 m0, s63
	v_lshl_add_u64 v[222:223], s[42:43], 0, v[130:131]
	global_load_lds_dwordx4 v132, s[46:47]
	s_mov_b32 m0, s62
	s_nop 0
	global_load_lds_dwordx4 v128, s[46:47]
	v_lshl_add_u64 v[220:221], s[42:43], 0, v[134:135]
	s_mov_b32 m0, s11
	s_nop 0
	global_load_lds_dwordx4 v[220:221], off
	s_mov_b32 m0, s14
	s_nop 0
	global_load_lds_dwordx4 v[222:223], off
	s_waitcnt vmcnt(8)
	s_waitcnt lgkmcnt(0)
	s_barrier
	s_setprio 1
	s_waitcnt lgkmcnt(0)
	v_mfma_f32_16x16x32_bf16 v[60:63], v[144:147], v[182:185], v[60:63]
	v_mfma_f32_16x16x32_bf16 v[56:59], v[158:161], v[182:185], v[56:59]
	v_mfma_f32_16x16x32_bf16 v[44:47], v[144:147], v[190:193], v[44:47]
	v_mfma_f32_16x16x32_bf16 v[40:43], v[158:161], v[190:193], v[40:43]
	v_mfma_f32_16x16x32_bf16 v[28:31], v[144:147], v[198:201], v[28:31]
	v_mfma_f32_16x16x32_bf16 v[24:27], v[158:161], v[198:201], v[24:27]
	v_mfma_f32_16x16x32_bf16 v[12:15], v[144:147], v[206:209], v[12:15]
	v_mfma_f32_16x16x32_bf16 v[8:11], v[158:161], v[206:209], v[8:11]
	v_mfma_f32_16x16x32_bf16 v[60:63], v[154:157], v[186:189], v[60:63]
	v_mfma_f32_16x16x32_bf16 v[56:59], v[162:165], v[186:189], v[56:59]
	v_mfma_f32_16x16x32_bf16 v[44:47], v[154:157], v[194:197], v[44:47]
	v_mfma_f32_16x16x32_bf16 v[40:43], v[162:165], v[194:197], v[40:43]
	v_mfma_f32_16x16x32_bf16 v[28:31], v[154:157], v[202:205], v[28:31]
	v_mfma_f32_16x16x32_bf16 v[24:27], v[162:165], v[202:205], v[24:27]
	v_mfma_f32_16x16x32_bf16 v[12:15], v[154:157], v[212:215], v[12:15]
	v_mfma_f32_16x16x32_bf16 v[8:11], v[162:165], v[212:215], v[8:11]
	s_setprio 0
	s_setprio 1
	v_mfma_f32_16x16x32_bf16 v[52:55], v[166:169], v[182:185], v[52:55]
	v_mfma_f32_16x16x32_bf16 v[48:51], v[174:177], v[182:185], v[48:51]
	v_mfma_f32_16x16x32_bf16 v[36:39], v[166:169], v[190:193], v[36:39]
	v_mfma_f32_16x16x32_bf16 v[32:35], v[174:177], v[190:193], v[32:35]
	v_mfma_f32_16x16x32_bf16 v[20:23], v[166:169], v[198:201], v[20:23]
	v_mfma_f32_16x16x32_bf16 v[16:19], v[174:177], v[198:201], v[16:19]
	v_mfma_f32_16x16x32_bf16 v[4:7], v[166:169], v[206:209], v[4:7]
	v_mfma_f32_16x16x32_bf16 v[0:3], v[174:177], v[206:209], v[0:3]
	v_mfma_f32_16x16x32_bf16 v[52:55], v[170:173], v[186:189], v[52:55]
	v_mfma_f32_16x16x32_bf16 v[48:51], v[178:181], v[186:189], v[48:51]
	v_mfma_f32_16x16x32_bf16 v[36:39], v[170:173], v[194:197], v[36:39]
	v_mfma_f32_16x16x32_bf16 v[32:35], v[178:181], v[194:197], v[32:35]
	v_mfma_f32_16x16x32_bf16 v[20:23], v[170:173], v[202:205], v[20:23]
	v_mfma_f32_16x16x32_bf16 v[16:19], v[178:181], v[202:205], v[16:19]
	v_mfma_f32_16x16x32_bf16 v[4:7], v[170:173], v[212:215], v[4:7]
	v_mfma_f32_16x16x32_bf16 v[0:3], v[178:181], v[212:215], v[0:3]
	s_setprio 0
	s_barrier
	v_add_u32_e32 v162, s60, v149
	v_add_u32_e32 v178, s59, v149
	ds_read_b128 v[144:147], v162
	ds_read_b128 v[154:157], v162 offset:1024
	ds_read_b128 v[158:161], v162 offset:2048
	ds_read_b128 v[162:165], v162 offset:3072
	ds_read_b128 v[166:169], v178
	ds_read_b128 v[170:173], v178 offset:1024
	ds_read_b128 v[174:177], v178 offset:2048
	ds_read_b128 v[178:181], v178 offset:3072
	s_mov_b32 m0, s15
	ds_read_b128 v[182:185], v152 offset:32768
	ds_read_b128 v[186:189], v152 offset:33792
	ds_read_b128 v[190:193], v152 offset:34816
	ds_read_b128 v[194:197], v152 offset:35840
	ds_read_b128 v[198:201], v152 offset:36864
	ds_read_b128 v[202:205], v152 offset:37888
	ds_read_b128 v[206:209], v152 offset:38912
	ds_read_b128 v[212:215], v152 offset:39936
	global_load_lds_dwordx4 v134, s[40:41]
	s_mov_b32 m0, s27
	s_nop 0
	global_load_lds_dwordx4 v130, s[40:41]
	s_waitcnt vmcnt(8)
	s_waitcnt lgkmcnt(0)
	s_barrier
	s_setprio 1
	s_waitcnt lgkmcnt(0)
	v_mfma_f32_16x16x32_bf16 v[124:127], v[144:147], v[182:185], v[124:127]
	v_mfma_f32_16x16x32_bf16 v[120:123], v[158:161], v[182:185], v[120:123]
	v_mfma_f32_16x16x32_bf16 v[108:111], v[144:147], v[190:193], v[108:111]
	v_mfma_f32_16x16x32_bf16 v[104:107], v[158:161], v[190:193], v[104:107]
	v_mfma_f32_16x16x32_bf16 v[92:95], v[144:147], v[198:201], v[92:95]
	v_mfma_f32_16x16x32_bf16 v[88:91], v[158:161], v[198:201], v[88:91]
	v_mfma_f32_16x16x32_bf16 v[76:79], v[144:147], v[206:209], v[76:79]
	v_mfma_f32_16x16x32_bf16 v[72:75], v[158:161], v[206:209], v[72:75]
	v_mfma_f32_16x16x32_bf16 v[124:127], v[154:157], v[186:189], v[124:127]
	v_mfma_f32_16x16x32_bf16 v[120:123], v[162:165], v[186:189], v[120:123]
	v_mfma_f32_16x16x32_bf16 v[108:111], v[154:157], v[194:197], v[108:111]
	v_mfma_f32_16x16x32_bf16 v[104:107], v[162:165], v[194:197], v[104:107]
	v_mfma_f32_16x16x32_bf16 v[92:95], v[154:157], v[202:205], v[92:95]
	v_mfma_f32_16x16x32_bf16 v[88:91], v[162:165], v[202:205], v[88:91]
	v_mfma_f32_16x16x32_bf16 v[76:79], v[154:157], v[212:215], v[76:79]
	v_mfma_f32_16x16x32_bf16 v[72:75], v[162:165], v[212:215], v[72:75]
	s_setprio 0
	s_setprio 1
	v_mfma_f32_16x16x32_bf16 v[116:119], v[166:169], v[182:185], v[116:119]
	v_mfma_f32_16x16x32_bf16 v[112:115], v[174:177], v[182:185], v[112:115]
	v_mfma_f32_16x16x32_bf16 v[100:103], v[166:169], v[190:193], v[100:103]
	v_mfma_f32_16x16x32_bf16 v[96:99], v[174:177], v[190:193], v[96:99]
	v_mfma_f32_16x16x32_bf16 v[84:87], v[166:169], v[198:201], v[84:87]
	v_mfma_f32_16x16x32_bf16 v[80:83], v[174:177], v[198:201], v[80:83]
	v_mfma_f32_16x16x32_bf16 v[68:71], v[166:169], v[206:209], v[68:71]
	v_mfma_f32_16x16x32_bf16 v[64:67], v[174:177], v[206:209], v[64:67]
	v_mfma_f32_16x16x32_bf16 v[116:119], v[170:173], v[186:189], v[116:119]
	v_mfma_f32_16x16x32_bf16 v[112:115], v[178:181], v[186:189], v[112:115]
	v_mfma_f32_16x16x32_bf16 v[100:103], v[170:173], v[194:197], v[100:103]
	v_mfma_f32_16x16x32_bf16 v[96:99], v[178:181], v[194:197], v[96:99]
	v_mfma_f32_16x16x32_bf16 v[84:87], v[170:173], v[202:205], v[84:87]
	v_mfma_f32_16x16x32_bf16 v[80:83], v[178:181], v[202:205], v[80:83]
	v_mfma_f32_16x16x32_bf16 v[68:71], v[170:173], v[212:215], v[68:71]
	v_mfma_f32_16x16x32_bf16 v[64:67], v[178:181], v[212:215], v[64:67]
	s_setprio 0
	s_barrier
	s_mov_b32 m0, s58
	v_lshl_add_u64 v[216:217], v[216:217], 0, s[2:3]
	ds_read_b128 v[182:185], v152 offset:49152
	ds_read_b128 v[186:189], v152 offset:50176
	ds_read_b128 v[190:193], v152 offset:51200
	ds_read_b128 v[194:197], v152 offset:52224
	ds_read_b128 v[198:201], v152 offset:53248
	ds_read_b128 v[202:205], v152 offset:54272
	ds_read_b128 v[206:209], v152 offset:55296
	ds_read_b128 v[212:215], v152 offset:56320
	global_load_lds_dwordx4 v[216:217], off
	v_lshl_add_u64 v[216:217], v[218:219], 0, s[2:3]
	s_mov_b32 m0, s56
	s_nop 0
	global_load_lds_dwordx4 v[216:217], off
	s_mov_b32 m0, s57
	s_nop 0
	global_load_lds_dwordx4 v132, s[38:39]
	s_mov_b32 m0, s55
	s_nop 0
	global_load_lds_dwordx4 v128, s[38:39]
	v_lshl_add_u64 v[216:217], v[220:221], 0, s[2:3]
	s_mov_b32 m0, s29
	s_nop 0
	global_load_lds_dwordx4 v[216:217], off
	v_lshl_add_u64 v[216:217], v[222:223], 0, s[2:3]
	s_mov_b32 m0, s33
	s_nop 0
	global_load_lds_dwordx4 v[216:217], off
	s_waitcnt vmcnt(8)
	s_waitcnt lgkmcnt(0)
	s_barrier
	s_setprio 1
	s_waitcnt lgkmcnt(0)
	v_mfma_f32_16x16x32_bf16 v[60:63], v[144:147], v[182:185], v[60:63]
	v_mfma_f32_16x16x32_bf16 v[56:59], v[158:161], v[182:185], v[56:59]
	v_mfma_f32_16x16x32_bf16 v[44:47], v[144:147], v[190:193], v[44:47]
	v_mfma_f32_16x16x32_bf16 v[40:43], v[158:161], v[190:193], v[40:43]
	v_mfma_f32_16x16x32_bf16 v[28:31], v[144:147], v[198:201], v[28:31]
	v_mfma_f32_16x16x32_bf16 v[24:27], v[158:161], v[198:201], v[24:27]
	v_mfma_f32_16x16x32_bf16 v[12:15], v[144:147], v[206:209], v[12:15]
	v_mfma_f32_16x16x32_bf16 v[8:11], v[158:161], v[206:209], v[8:11]
	v_mfma_f32_16x16x32_bf16 v[60:63], v[154:157], v[186:189], v[60:63]
	v_mfma_f32_16x16x32_bf16 v[56:59], v[162:165], v[186:189], v[56:59]
	v_mfma_f32_16x16x32_bf16 v[44:47], v[154:157], v[194:197], v[44:47]
	v_mfma_f32_16x16x32_bf16 v[40:43], v[162:165], v[194:197], v[40:43]
	v_mfma_f32_16x16x32_bf16 v[28:31], v[154:157], v[202:205], v[28:31]
	v_mfma_f32_16x16x32_bf16 v[24:27], v[162:165], v[202:205], v[24:27]
	v_mfma_f32_16x16x32_bf16 v[12:15], v[154:157], v[212:215], v[12:15]
	v_mfma_f32_16x16x32_bf16 v[8:11], v[162:165], v[212:215], v[8:11]
	s_setprio 0
	s_setprio 1
	v_mfma_f32_16x16x32_bf16 v[52:55], v[166:169], v[182:185], v[52:55]
	v_mfma_f32_16x16x32_bf16 v[48:51], v[174:177], v[182:185], v[48:51]
	v_mfma_f32_16x16x32_bf16 v[36:39], v[166:169], v[190:193], v[36:39]
	v_mfma_f32_16x16x32_bf16 v[32:35], v[174:177], v[190:193], v[32:35]
	v_mfma_f32_16x16x32_bf16 v[20:23], v[166:169], v[198:201], v[20:23]
	v_mfma_f32_16x16x32_bf16 v[16:19], v[174:177], v[198:201], v[16:19]
	v_mfma_f32_16x16x32_bf16 v[4:7], v[166:169], v[206:209], v[4:7]
	v_mfma_f32_16x16x32_bf16 v[0:3], v[174:177], v[206:209], v[0:3]
	v_mfma_f32_16x16x32_bf16 v[52:55], v[170:173], v[186:189], v[52:55]
	v_mfma_f32_16x16x32_bf16 v[48:51], v[178:181], v[186:189], v[48:51]
	v_mfma_f32_16x16x32_bf16 v[36:39], v[170:173], v[194:197], v[36:39]
	v_mfma_f32_16x16x32_bf16 v[32:35], v[178:181], v[194:197], v[32:35]
	v_mfma_f32_16x16x32_bf16 v[20:23], v[170:173], v[202:205], v[20:23]
	v_mfma_f32_16x16x32_bf16 v[16:19], v[178:181], v[202:205], v[16:19]
	v_mfma_f32_16x16x32_bf16 v[4:7], v[170:173], v[212:215], v[4:7]
	v_mfma_f32_16x16x32_bf16 v[0:3], v[178:181], v[212:215], v[0:3]
	s_setprio 0
	s_barrier
	s_andn2_b64 vcc, exec, s[36:37]
	s_mov_b64 s[38:39], -1
	s_mov_b64 s[36:37], 0
	s_mov_b64 s[40:41], 0x100
	s_cbranch_vccz .LBB0_894
	s_and_b64 vcc, exec, s[6:7]
	s_cbranch_vccz .LBB0_897
	s_barrier

.LBB0_1155:
	v_add_u32_e32 v1, s46, v193
	ds_read_b128 v[72:75], v1
	ds_read_b128 v[76:79], v1 offset:1024
	ds_read_b128 v[84:87], v1 offset:2048
	ds_read_b128 v[188:191], v1 offset:3072
	v_add_u32_e32 v1, s47, v193
	s_add_u32 s34, s28, s30
	ds_read_b128 v[198:201], v1
	ds_read_b128 v[202:205], v1 offset:1024
	ds_read_b128 v[206:209], v1 offset:2048
	ds_read_b128 v[210:213], v1 offset:3072
	s_addc_u32 s35, s29, s31
	s_add_u32 s34, s34, 0x100
	s_addc_u32 s35, s35, 0
	s_add_u32 s53, s50, s30
	s_addc_u32 s54, s51, s31
	s_cmpk_eq_i32 s30, 0x700
	s_cselect_b32 s37, s21, s35
	s_cselect_b32 s36, s27, s34
	s_cselect_b32 s35, s19, s54
	s_cselect_b32 s34, s49, s53
	v_lshl_add_u64 v[2:3], v[112:113], 0, s[30:31]
	s_add_i32 m0, s38, 0xc000
	ds_read_b128 v[216:219], v197
	ds_read_b128 v[220:223], v197 offset:1024
	ds_read_b128 v[224:227], v197 offset:2048
	ds_read_b128 v[228:231], v197 offset:3072
	ds_read_b128 v[232:235], v197 offset:4096
	ds_read_b128 v[236:239], v197 offset:5120
	ds_read_b128 v[240:243], v197 offset:6144
	ds_read_b128 v[244:247], v197 offset:7168
	global_load_lds_dwordx4 v[2:3], off
	v_lshl_add_u64 v[2:3], v[114:115], 0, s[30:31]
	s_add_i32 m0, s38, 0xe000
	s_nop 0
	global_load_lds_dwordx4 v[2:3], off
	s_waitcnt vmcnt(8)
	s_waitcnt lgkmcnt(0)
	s_barrier
	s_setprio 1
	s_waitcnt lgkmcnt(0)
	v_mfma_f32_16x16x32_bf16 v[156:159], v[72:75], v[216:219], v[156:159]
	v_mfma_f32_16x16x32_bf16 v[160:163], v[84:87], v[216:219], v[160:163]
	v_mfma_f32_16x16x32_bf16 v[144:147], v[72:75], v[224:227], v[144:147]
	v_mfma_f32_16x16x32_bf16 v[140:143], v[84:87], v[224:227], v[140:143]
	v_mfma_f32_16x16x32_bf16 v[128:131], v[72:75], v[232:235], v[128:131]
	v_mfma_f32_16x16x32_bf16 v[124:127], v[84:87], v[232:235], v[124:127]
	v_mfma_f32_16x16x32_bf16 v[96:99], v[72:75], v[240:243], v[96:99]
	v_mfma_f32_16x16x32_bf16 v[92:95], v[84:87], v[240:243], v[92:95]
	v_mfma_f32_16x16x32_bf16 v[156:159], v[76:79], v[220:223], v[156:159]
	v_mfma_f32_16x16x32_bf16 v[160:163], v[188:191], v[220:223], v[160:163]
	v_mfma_f32_16x16x32_bf16 v[144:147], v[76:79], v[228:231], v[144:147]
	v_mfma_f32_16x16x32_bf16 v[140:143], v[188:191], v[228:231], v[140:143]
	v_mfma_f32_16x16x32_bf16 v[128:131], v[76:79], v[236:239], v[128:131]
	v_mfma_f32_16x16x32_bf16 v[124:127], v[188:191], v[236:239], v[124:127]
	v_mfma_f32_16x16x32_bf16 v[96:99], v[76:79], v[244:247], v[96:99]
	v_mfma_f32_16x16x32_bf16 v[92:95], v[188:191], v[244:247], v[92:95]
	s_setprio 0
	s_setprio 1
	v_mfma_f32_16x16x32_bf16 v[152:155], v[198:201], v[216:219], v[152:155]
	v_mfma_f32_16x16x32_bf16 v[148:151], v[206:209], v[216:219], v[148:151]
	v_mfma_f32_16x16x32_bf16 v[136:139], v[198:201], v[224:227], v[136:139]
	v_mfma_f32_16x16x32_bf16 v[132:135], v[206:209], v[224:227], v[132:135]
	v_mfma_f32_16x16x32_bf16 v[120:123], v[198:201], v[232:235], v[120:123]
	v_mfma_f32_16x16x32_bf16 v[116:119], v[206:209], v[232:235], v[116:119]
	v_mfma_f32_16x16x32_bf16 v[80:83], v[198:201], v[240:243], v[80:83]
	v_mfma_f32_16x16x32_bf16 v[68:71], v[206:209], v[240:243], v[68:71]
	v_mfma_f32_16x16x32_bf16 v[152:155], v[202:205], v[220:223], v[152:155]
	v_mfma_f32_16x16x32_bf16 v[148:151], v[210:213], v[220:223], v[148:151]
	v_mfma_f32_16x16x32_bf16 v[136:139], v[202:205], v[228:231], v[136:139]
	v_mfma_f32_16x16x32_bf16 v[132:135], v[210:213], v[228:231], v[132:135]
	v_mfma_f32_16x16x32_bf16 v[120:123], v[202:205], v[236:239], v[120:123]
	v_mfma_f32_16x16x32_bf16 v[116:119], v[210:213], v[236:239], v[116:119]
	v_mfma_f32_16x16x32_bf16 v[80:83], v[202:205], v[244:247], v[80:83]
	v_mfma_f32_16x16x32_bf16 v[68:71], v[210:213], v[244:247], v[68:71]
	s_setprio 0
	s_barrier
	s_add_i32 s53, s46, s33
	v_lshl_add_u64 v[248:249], s[34:35], 0, v[166:167]
	s_mov_b32 m0, s53
	ds_read_b128 v[216:219], v197 offset:16384
	ds_read_b128 v[220:223], v197 offset:17408
	ds_read_b128 v[224:227], v197 offset:18432
	ds_read_b128 v[228:231], v197 offset:19456
	ds_read_b128 v[232:235], v197 offset:20480
	ds_read_b128 v[236:239], v197 offset:21504
	ds_read_b128 v[240:243], v197 offset:22528
	ds_read_b128 v[244:247], v197 offset:23552
	global_load_lds_dwordx4 v[248:249], off
	s_add_i32 m0, s53, 0x2000
	s_add_u32 s54, s34, 0x40000
	v_lshl_add_u64 v[250:251], s[34:35], 0, v[170:171]
	s_addc_u32 s55, s35, 0
	s_add_i32 s53, s47, s33
	global_load_lds_dwordx4 v[250:251], off
	s_mov_b32 m0, s53
	v_lshl_add_u64 v[252:253], s[36:37], 0, v[164:165]
	global_load_lds_dwordx4 v166, s[54:55]
	s_add_i32 m0, s53, 0x2000
	v_lshl_add_u64 v[176:177], s[36:37], 0, v[168:169]
	global_load_lds_dwordx4 v170, s[54:55]
	s_mov_b32 m0, s38
	s_nop 0
	global_load_lds_dwordx4 v[252:253], off
	s_mov_b32 m0, s39
	s_nop 0
	global_load_lds_dwordx4 v[176:177], off
	s_waitcnt vmcnt(8)
	s_waitcnt lgkmcnt(0)
	s_barrier
	s_setprio 1
	s_waitcnt lgkmcnt(0)
	v_mfma_f32_16x16x32_bf16 v[64:67], v[72:75], v[216:219], v[64:67]
	v_mfma_f32_16x16x32_bf16 v[60:63], v[84:87], v[216:219], v[60:63]
	v_mfma_f32_16x16x32_bf16 v[48:51], v[72:75], v[224:227], v[48:51]
	v_mfma_f32_16x16x32_bf16 v[44:47], v[84:87], v[224:227], v[44:47]
	v_mfma_f32_16x16x32_bf16 v[32:35], v[72:75], v[232:235], v[32:35]
	v_mfma_f32_16x16x32_bf16 v[28:31], v[84:87], v[232:235], v[28:31]
	v_mfma_f32_16x16x32_bf16 v[16:19], v[72:75], v[240:243], v[16:19]
	v_mfma_f32_16x16x32_bf16 v[12:15], v[84:87], v[240:243], v[12:15]
	v_mfma_f32_16x16x32_bf16 v[64:67], v[76:79], v[220:223], v[64:67]
	v_mfma_f32_16x16x32_bf16 v[60:63], v[188:191], v[220:223], v[60:63]
	v_mfma_f32_16x16x32_bf16 v[48:51], v[76:79], v[228:231], v[48:51]
	v_mfma_f32_16x16x32_bf16 v[44:47], v[188:191], v[228:231], v[44:47]
	v_mfma_f32_16x16x32_bf16 v[32:35], v[76:79], v[236:239], v[32:35]
	v_mfma_f32_16x16x32_bf16 v[28:31], v[188:191], v[236:239], v[28:31]
	v_mfma_f32_16x16x32_bf16 v[16:19], v[76:79], v[244:247], v[16:19]
	v_mfma_f32_16x16x32_bf16 v[12:15], v[188:191], v[244:247], v[12:15]
	s_setprio 0
	s_setprio 1
	v_mfma_f32_16x16x32_bf16 v[56:59], v[198:201], v[216:219], v[56:59]
	v_mfma_f32_16x16x32_bf16 v[52:55], v[206:209], v[216:219], v[52:55]
	v_mfma_f32_16x16x32_bf16 v[40:43], v[198:201], v[224:227], v[40:43]
	v_mfma_f32_16x16x32_bf16 v[36:39], v[206:209], v[224:227], v[36:39]
	v_mfma_f32_16x16x32_bf16 v[24:27], v[198:201], v[232:235], v[24:27]
	v_mfma_f32_16x16x32_bf16 v[20:23], v[206:209], v[232:235], v[20:23]
	v_mfma_f32_16x16x32_bf16 v[8:11], v[198:201], v[240:243], v[8:11]
	v_mfma_f32_16x16x32_bf16 v[2:5], v[206:209], v[240:243], v[4:7]
	v_mfma_f32_16x16x32_bf16 v[56:59], v[202:205], v[220:223], v[56:59]
	v_mfma_f32_16x16x32_bf16 v[52:55], v[210:213], v[220:223], v[52:55]
	v_mfma_f32_16x16x32_bf16 v[40:43], v[202:205], v[228:231], v[40:43]
	v_mfma_f32_16x16x32_bf16 v[36:39], v[210:213], v[228:231], v[36:39]
	v_mfma_f32_16x16x32_bf16 v[24:27], v[202:205], v[236:239], v[24:27]
	v_mfma_f32_16x16x32_bf16 v[20:23], v[210:213], v[236:239], v[20:23]
	v_mfma_f32_16x16x32_bf16 v[8:11], v[202:205], v[244:247], v[8:11]
	v_mfma_f32_16x16x32_bf16 v[2:5], v[210:213], v[244:247], v[2:5]
	s_setprio 0
	s_barrier
	s_add_i32 s53, 0, 0x18000
	v_add_u32_e32 v1, s53, v193
	s_add_i32 s54, 0, 0x1c000
	ds_read_b128 v[72:75], v1
	ds_read_b128 v[76:79], v1 offset:1024
	ds_read_b128 v[84:87], v1 offset:2048
	ds_read_b128 v[188:191], v1 offset:3072
	v_add_u32_e32 v1, s54, v193
	ds_read_b128 v[198:201], v1
	ds_read_b128 v[202:205], v1 offset:1024
	ds_read_b128 v[206:209], v1 offset:2048
	ds_read_b128 v[210:213], v1 offset:3072
	s_add_u32 s36, s36, 0x40000
	s_addc_u32 s37, s37, 0
	s_mov_b32 m0, s40
	ds_read_b128 v[216:219], v197 offset:32768
	ds_read_b128 v[220:223], v197 offset:33792
	ds_read_b128 v[224:227], v197 offset:34816
	ds_read_b128 v[228:231], v197 offset:35840
	ds_read_b128 v[232:235], v197 offset:36864
	ds_read_b128 v[236:239], v197 offset:37888
	ds_read_b128 v[240:243], v197 offset:38912
	ds_read_b128 v[244:247], v197 offset:39936
	global_load_lds_dwordx4 v164, s[36:37]
	s_mov_b32 m0, s41
	s_nop 0
	global_load_lds_dwordx4 v168, s[36:37]
	s_waitcnt vmcnt(8)
	s_waitcnt lgkmcnt(0)
	s_barrier
	s_setprio 1
	s_waitcnt lgkmcnt(0)
	v_mfma_f32_16x16x32_bf16 v[156:159], v[72:75], v[216:219], v[156:159]
	v_mfma_f32_16x16x32_bf16 v[160:163], v[84:87], v[216:219], v[160:163]
	v_mfma_f32_16x16x32_bf16 v[144:147], v[72:75], v[224:227], v[144:147]
	v_mfma_f32_16x16x32_bf16 v[140:143], v[84:87], v[224:227], v[140:143]
	v_mfma_f32_16x16x32_bf16 v[128:131], v[72:75], v[232:235], v[128:131]
	v_mfma_f32_16x16x32_bf16 v[124:127], v[84:87], v[232:235], v[124:127]
	v_mfma_f32_16x16x32_bf16 v[96:99], v[72:75], v[240:243], v[96:99]
	v_mfma_f32_16x16x32_bf16 v[92:95], v[84:87], v[240:243], v[92:95]
	v_mfma_f32_16x16x32_bf16 v[156:159], v[76:79], v[220:223], v[156:159]
	v_mfma_f32_16x16x32_bf16 v[160:163], v[188:191], v[220:223], v[160:163]
	v_mfma_f32_16x16x32_bf16 v[144:147], v[76:79], v[228:231], v[144:147]
	v_mfma_f32_16x16x32_bf16 v[140:143], v[188:191], v[228:231], v[140:143]
	v_mfma_f32_16x16x32_bf16 v[128:131], v[76:79], v[236:239], v[128:131]
	v_mfma_f32_16x16x32_bf16 v[124:127], v[188:191], v[236:239], v[124:127]
	v_mfma_f32_16x16x32_bf16 v[96:99], v[76:79], v[244:247], v[96:99]
	v_mfma_f32_16x16x32_bf16 v[92:95], v[188:191], v[244:247], v[92:95]
	s_setprio 0
	s_setprio 1
	v_mfma_f32_16x16x32_bf16 v[152:155], v[198:201], v[216:219], v[152:155]
	v_mfma_f32_16x16x32_bf16 v[148:151], v[206:209], v[216:219], v[148:151]
	v_mfma_f32_16x16x32_bf16 v[136:139], v[198:201], v[224:227], v[136:139]
	v_mfma_f32_16x16x32_bf16 v[132:135], v[206:209], v[224:227], v[132:135]
	v_mfma_f32_16x16x32_bf16 v[120:123], v[198:201], v[232:235], v[120:123]
	v_mfma_f32_16x16x32_bf16 v[116:119], v[206:209], v[232:235], v[116:119]
	v_mfma_f32_16x16x32_bf16 v[80:83], v[198:201], v[240:243], v[80:83]
	v_mfma_f32_16x16x32_bf16 v[68:71], v[206:209], v[240:243], v[68:71]
	v_mfma_f32_16x16x32_bf16 v[152:155], v[202:205], v[220:223], v[152:155]
	v_mfma_f32_16x16x32_bf16 v[148:151], v[210:213], v[220:223], v[148:151]
	v_mfma_f32_16x16x32_bf16 v[136:139], v[202:205], v[228:231], v[136:139]
	v_mfma_f32_16x16x32_bf16 v[132:135], v[210:213], v[228:231], v[132:135]
	v_mfma_f32_16x16x32_bf16 v[120:123], v[202:205], v[236:239], v[120:123]
	v_mfma_f32_16x16x32_bf16 v[116:119], v[210:213], v[236:239], v[116:119]
	v_mfma_f32_16x16x32_bf16 v[80:83], v[202:205], v[244:247], v[80:83]
	v_mfma_f32_16x16x32_bf16 v[68:71], v[210:213], v[244:247], v[68:71]
	s_setprio 0
	s_barrier
	s_add_i32 s36, s53, s33
	v_lshl_add_u64 v[6:7], v[248:249], 0, s[10:11]
	s_mov_b32 m0, s36
	ds_read_b128 v[216:219], v197 offset:49152
	ds_read_b128 v[220:223], v197 offset:50176
	ds_read_b128 v[224:227], v197 offset:51200
	ds_read_b128 v[228:231], v197 offset:52224
	ds_read_b128 v[232:235], v197 offset:53248
	ds_read_b128 v[236:239], v197 offset:54272
	ds_read_b128 v[240:243], v197 offset:55296
	ds_read_b128 v[244:247], v197 offset:56320
	global_load_lds_dwordx4 v[6:7], off
	s_add_i32 m0, s36, 0x2000
	s_add_u32 s34, s34, 0x40080
	v_lshl_add_u64 v[6:7], v[250:251], 0, s[10:11]
	s_addc_u32 s35, s35, 0
	s_add_i32 s36, s54, s33
	global_load_lds_dwordx4 v[6:7], off
	s_mov_b32 m0, s36
	s_nop 0
	global_load_lds_dwordx4 v166, s[34:35]
	s_add_i32 m0, s36, 0x2000
	s_nop 0
	global_load_lds_dwordx4 v170, s[34:35]
	v_lshl_add_u64 v[6:7], v[252:253], 0, s[10:11]
	s_mov_b32 m0, s43
	s_nop 0
	global_load_lds_dwordx4 v[6:7], off
	v_lshl_add_u64 v[6:7], v[176:177], 0, s[10:11]
	s_mov_b32 m0, s44
	s_nop 0
	global_load_lds_dwordx4 v[6:7], off
	s_waitcnt vmcnt(8)
	s_waitcnt lgkmcnt(0)
	s_barrier
	s_setprio 1
	s_waitcnt lgkmcnt(0)
	v_mfma_f32_16x16x32_bf16 v[64:67], v[72:75], v[216:219], v[64:67]
	v_mfma_f32_16x16x32_bf16 v[60:63], v[84:87], v[216:219], v[60:63]
	v_mfma_f32_16x16x32_bf16 v[48:51], v[72:75], v[224:227], v[48:51]
	v_mfma_f32_16x16x32_bf16 v[44:47], v[84:87], v[224:227], v[44:47]
	v_mfma_f32_16x16x32_bf16 v[32:35], v[72:75], v[232:235], v[32:35]
	v_mfma_f32_16x16x32_bf16 v[28:31], v[84:87], v[232:235], v[28:31]
	v_mfma_f32_16x16x32_bf16 v[16:19], v[72:75], v[240:243], v[16:19]
	v_mfma_f32_16x16x32_bf16 v[12:15], v[84:87], v[240:243], v[12:15]
	v_mfma_f32_16x16x32_bf16 v[64:67], v[76:79], v[220:223], v[64:67]
	v_mfma_f32_16x16x32_bf16 v[60:63], v[188:191], v[220:223], v[60:63]
	v_mfma_f32_16x16x32_bf16 v[48:51], v[76:79], v[228:231], v[48:51]
	v_mfma_f32_16x16x32_bf16 v[44:47], v[188:191], v[228:231], v[44:47]
	v_mfma_f32_16x16x32_bf16 v[32:35], v[76:79], v[236:239], v[32:35]
	v_mfma_f32_16x16x32_bf16 v[28:31], v[188:191], v[236:239], v[28:31]
	v_mfma_f32_16x16x32_bf16 v[16:19], v[76:79], v[244:247], v[16:19]
	v_mfma_f32_16x16x32_bf16 v[12:15], v[188:191], v[244:247], v[12:15]
	s_setprio 0
	s_setprio 1
	v_mfma_f32_16x16x32_bf16 v[56:59], v[198:201], v[216:219], v[56:59]
	v_mfma_f32_16x16x32_bf16 v[52:55], v[206:209], v[216:219], v[52:55]
	v_mfma_f32_16x16x32_bf16 v[40:43], v[198:201], v[224:227], v[40:43]
	v_mfma_f32_16x16x32_bf16 v[36:39], v[206:209], v[224:227], v[36:39]
	v_mfma_f32_16x16x32_bf16 v[24:27], v[198:201], v[232:235], v[24:27]
	v_mfma_f32_16x16x32_bf16 v[20:23], v[206:209], v[232:235], v[20:23]
	v_mfma_f32_16x16x32_bf16 v[6:9], v[198:201], v[240:243], v[8:11]
	v_mfma_f32_16x16x32_bf16 v[2:5], v[206:209], v[240:243], v[2:5]
	v_mfma_f32_16x16x32_bf16 v[56:59], v[202:205], v[220:223], v[56:59]
	v_mfma_f32_16x16x32_bf16 v[52:55], v[210:213], v[220:223], v[52:55]
	v_mfma_f32_16x16x32_bf16 v[40:43], v[202:205], v[228:231], v[40:43]
	v_mfma_f32_16x16x32_bf16 v[36:39], v[210:213], v[228:231], v[36:39]
	v_mfma_f32_16x16x32_bf16 v[24:27], v[202:205], v[236:239], v[24:27]
	v_mfma_f32_16x16x32_bf16 v[20:23], v[210:213], v[236:239], v[20:23]
	v_mfma_f32_16x16x32_bf16 v[8:11], v[202:205], v[244:247], v[6:9]
	v_mfma_f32_16x16x32_bf16 v[4:7], v[210:213], v[244:247], v[2:5]
	s_setprio 0
	s_barrier
	s_add_i32 s52, s52, 2
	s_add_u32 s30, s30, 0x100
	s_addc_u32 s31, s31, 0
	s_cmp_gt_u32 s52, 13
	s_cbranch_scc1 .LBB0_1158

.LBB0_1243:
	ds_read_b128 v[128:131], v183
	ds_read_b128 v[132:135], v183 offset:1024
	ds_read_b128 v[136:139], v183 offset:2048
	ds_read_b128 v[140:143], v183 offset:3072
	ds_read_b128 v[144:147], v184
	ds_read_b128 v[164:167], v184 offset:1024
	ds_read_b128 v[168:171], v184 offset:2048
	ds_read_b128 v[172:175], v184 offset:3072
	s_add_u32 s20, s18, 0xfffc0080
	s_addc_u32 s21, s19, -1
	s_cmp_eq_u32 s44, 12
	s_cselect_b32 s23, s13, s21
	s_cselect_b32 s22, s40, s20
	s_cselect_b32 s21, s11, s43
	s_cselect_b32 s20, s41, s42
	s_add_i32 m0, s25, 0xc000
	ds_read_b128 v[176:179], v185
	ds_read_b128 v[188:191], v185 offset:1024
	ds_read_b128 v[192:195], v185 offset:2048
	ds_read_b128 v[196:199], v185 offset:3072
	ds_read_b128 v[200:203], v185 offset:4096
	ds_read_b128 v[204:207], v185 offset:5120
	ds_read_b128 v[208:211], v185 offset:6144
	ds_read_b128 v[216:219], v185 offset:7168
	global_load_lds_dwordx4 v156, s[18:19]
	s_add_i32 m0, s25, 0xe000
	s_nop 0
	global_load_lds_dwordx4 v158, s[18:19]
	s_waitcnt vmcnt(8)
	s_waitcnt lgkmcnt(0)
	s_barrier
	s_setprio 1
	s_waitcnt lgkmcnt(0)
	v_mfma_f32_16x16x32_bf16 v[124:127], v[128:131], v[176:179], v[124:127]
	v_mfma_f32_16x16x32_bf16 v[120:123], v[136:139], v[176:179], v[120:123]
	v_mfma_f32_16x16x32_bf16 v[116:119], v[128:131], v[192:195], v[116:119]
	v_mfma_f32_16x16x32_bf16 v[112:115], v[136:139], v[192:195], v[112:115]
	v_mfma_f32_16x16x32_bf16 v[108:111], v[128:131], v[200:203], v[108:111]
	v_mfma_f32_16x16x32_bf16 v[100:103], v[136:139], v[200:203], v[100:103]
	v_mfma_f32_16x16x32_bf16 v[88:91], v[128:131], v[208:211], v[88:91]
	v_mfma_f32_16x16x32_bf16 v[80:83], v[136:139], v[208:211], v[80:83]
	v_mfma_f32_16x16x32_bf16 v[124:127], v[132:135], v[188:191], v[124:127]
	v_mfma_f32_16x16x32_bf16 v[120:123], v[140:143], v[188:191], v[120:123]
	v_mfma_f32_16x16x32_bf16 v[116:119], v[132:135], v[196:199], v[116:119]
	v_mfma_f32_16x16x32_bf16 v[112:115], v[140:143], v[196:199], v[112:115]
	v_mfma_f32_16x16x32_bf16 v[108:111], v[132:135], v[204:207], v[108:111]
	v_mfma_f32_16x16x32_bf16 v[100:103], v[140:143], v[204:207], v[100:103]
	v_mfma_f32_16x16x32_bf16 v[88:91], v[132:135], v[216:219], v[88:91]
	v_mfma_f32_16x16x32_bf16 v[80:83], v[140:143], v[216:219], v[80:83]
	s_setprio 0
	s_setprio 1
	v_mfma_f32_16x16x32_bf16 v[104:107], v[144:147], v[176:179], v[104:107]
	v_mfma_f32_16x16x32_bf16 v[96:99], v[168:171], v[176:179], v[96:99]
	v_mfma_f32_16x16x32_bf16 v[92:95], v[144:147], v[192:195], v[92:95]
	v_mfma_f32_16x16x32_bf16 v[84:87], v[168:171], v[192:195], v[84:87]
	v_mfma_f32_16x16x32_bf16 v[76:79], v[144:147], v[200:203], v[76:79]
	v_mfma_f32_16x16x32_bf16 v[72:75], v[168:171], v[200:203], v[72:75]
	v_mfma_f32_16x16x32_bf16 v[68:71], v[144:147], v[208:211], v[68:71]
	v_mfma_f32_16x16x32_bf16 v[64:67], v[168:171], v[208:211], v[64:67]
	v_mfma_f32_16x16x32_bf16 v[104:107], v[164:167], v[188:191], v[104:107]
	v_mfma_f32_16x16x32_bf16 v[96:99], v[172:175], v[188:191], v[96:99]
	v_mfma_f32_16x16x32_bf16 v[92:95], v[164:167], v[196:199], v[92:95]
	v_mfma_f32_16x16x32_bf16 v[84:87], v[172:175], v[196:199], v[84:87]
	v_mfma_f32_16x16x32_bf16 v[76:79], v[164:167], v[204:207], v[76:79]
	v_mfma_f32_16x16x32_bf16 v[72:75], v[172:175], v[204:207], v[72:75]
	v_mfma_f32_16x16x32_bf16 v[68:71], v[164:167], v[216:219], v[68:71]
	v_mfma_f32_16x16x32_bf16 v[64:67], v[172:175], v[216:219], v[64:67]
	s_setprio 0
	s_barrier
	s_add_i32 s45, s36, s24
	v_lshl_add_u64 v[212:213], s[20:21], 0, v[152:153]
	s_mov_b32 m0, s45
	ds_read_b128 v[176:179], v185 offset:16384
	ds_read_b128 v[188:191], v185 offset:17408
	ds_read_b128 v[192:195], v185 offset:18432
	ds_read_b128 v[196:199], v185 offset:19456
	ds_read_b128 v[200:203], v185 offset:20480
	ds_read_b128 v[204:207], v185 offset:21504
	ds_read_b128 v[208:211], v185 offset:22528
	ds_read_b128 v[216:219], v185 offset:23552
	global_load_lds_dwordx4 v[212:213], off
	s_add_i32 m0, s45, 0x2000
	s_add_u32 s46, s20, 0x40000
	v_lshl_add_u64 v[220:221], s[20:21], 0, v[148:149]
	s_addc_u32 s47, s21, 0
	s_add_i32 s45, s37, s24
	global_load_lds_dwordx4 v[220:221], off
	s_mov_b32 m0, s45
	v_lshl_add_u64 v[224:225], s[22:23], 0, v[150:151]
	global_load_lds_dwordx4 v152, s[46:47]
	s_add_i32 m0, s45, 0x2000
	s_nop 0
	global_load_lds_dwordx4 v148, s[46:47]
	v_lshl_add_u64 v[222:223], s[22:23], 0, v[154:155]
	s_mov_b32 m0, s25
	s_nop 0
	global_load_lds_dwordx4 v[222:223], off
	s_mov_b32 m0, s26
	s_nop 0
	global_load_lds_dwordx4 v[224:225], off
	s_waitcnt vmcnt(8)
	s_waitcnt lgkmcnt(0)
	s_barrier
	s_setprio 1
	s_waitcnt lgkmcnt(0)
	v_mfma_f32_16x16x32_bf16 v[60:63], v[128:131], v[176:179], v[60:63]
	v_mfma_f32_16x16x32_bf16 v[56:59], v[136:139], v[176:179], v[56:59]
	v_mfma_f32_16x16x32_bf16 v[52:55], v[128:131], v[192:195], v[52:55]
	v_mfma_f32_16x16x32_bf16 v[48:51], v[136:139], v[192:195], v[48:51]
	v_mfma_f32_16x16x32_bf16 v[40:43], v[128:131], v[200:203], v[40:43]
	v_mfma_f32_16x16x32_bf16 v[32:35], v[136:139], v[200:203], v[32:35]
	v_mfma_f32_16x16x32_bf16 v[20:23], v[128:131], v[208:211], v[20:23]
	v_mfma_f32_16x16x32_bf16 v[16:19], v[136:139], v[208:211], v[16:19]
	v_mfma_f32_16x16x32_bf16 v[60:63], v[132:135], v[188:191], v[60:63]
	v_mfma_f32_16x16x32_bf16 v[56:59], v[140:143], v[188:191], v[56:59]
	v_mfma_f32_16x16x32_bf16 v[52:55], v[132:135], v[196:199], v[52:55]
	v_mfma_f32_16x16x32_bf16 v[48:51], v[140:143], v[196:199], v[48:51]
	v_mfma_f32_16x16x32_bf16 v[40:43], v[132:135], v[204:207], v[40:43]
	v_mfma_f32_16x16x32_bf16 v[32:35], v[140:143], v[204:207], v[32:35]
	v_mfma_f32_16x16x32_bf16 v[20:23], v[132:135], v[216:219], v[20:23]
	v_mfma_f32_16x16x32_bf16 v[16:19], v[140:143], v[216:219], v[16:19]
	s_setprio 0
	s_setprio 1
	v_mfma_f32_16x16x32_bf16 v[44:47], v[144:147], v[176:179], v[44:47]
	v_mfma_f32_16x16x32_bf16 v[36:39], v[168:171], v[176:179], v[36:39]
	v_mfma_f32_16x16x32_bf16 v[28:31], v[144:147], v[192:195], v[28:31]
	v_mfma_f32_16x16x32_bf16 v[24:27], v[168:171], v[192:195], v[24:27]
	v_mfma_f32_16x16x32_bf16 v[12:15], v[144:147], v[200:203], v[12:15]
	v_mfma_f32_16x16x32_bf16 v[8:11], v[168:171], v[200:203], v[8:11]
	v_mfma_f32_16x16x32_bf16 v[4:7], v[144:147], v[208:211], v[4:7]
	v_mfma_f32_16x16x32_bf16 v[0:3], v[168:171], v[208:211], v[0:3]
	v_mfma_f32_16x16x32_bf16 v[44:47], v[164:167], v[188:191], v[44:47]
	v_mfma_f32_16x16x32_bf16 v[36:39], v[172:175], v[188:191], v[36:39]
	v_mfma_f32_16x16x32_bf16 v[28:31], v[164:167], v[196:199], v[28:31]
	v_mfma_f32_16x16x32_bf16 v[24:27], v[172:175], v[196:199], v[24:27]
	v_mfma_f32_16x16x32_bf16 v[12:15], v[164:167], v[204:207], v[12:15]
	v_mfma_f32_16x16x32_bf16 v[8:11], v[172:175], v[204:207], v[8:11]
	v_mfma_f32_16x16x32_bf16 v[4:7], v[164:167], v[216:219], v[4:7]
	v_mfma_f32_16x16x32_bf16 v[0:3], v[172:175], v[216:219], v[0:3]
	s_setprio 0
	s_barrier
	s_add_i32 s45, 0, 0x18000
	s_add_i32 s46, 0, 0x1c000
	v_add_u32_e32 v140, s45, v181
	v_add_u32_e32 v172, s46, v181
	ds_read_b128 v[128:131], v140
	ds_read_b128 v[132:135], v140 offset:1024
	ds_read_b128 v[136:139], v140 offset:2048
	ds_read_b128 v[140:143], v140 offset:3072
	ds_read_b128 v[144:147], v172
	ds_read_b128 v[164:167], v172 offset:1024
	ds_read_b128 v[168:171], v172 offset:2048
	ds_read_b128 v[172:175], v172 offset:3072
	s_add_u32 s22, s22, 0x40000
	s_addc_u32 s23, s23, 0
	s_mov_b32 m0, s27
	ds_read_b128 v[176:179], v185 offset:32768
	ds_read_b128 v[188:191], v185 offset:33792
	ds_read_b128 v[192:195], v185 offset:34816
	ds_read_b128 v[196:199], v185 offset:35840
	ds_read_b128 v[200:203], v185 offset:36864
	ds_read_b128 v[204:207], v185 offset:37888
	ds_read_b128 v[208:211], v185 offset:38912
	ds_read_b128 v[216:219], v185 offset:39936
	global_load_lds_dwordx4 v154, s[22:23]
	s_mov_b32 m0, s28
	s_nop 0
	global_load_lds_dwordx4 v150, s[22:23]
	s_waitcnt vmcnt(8)
	s_waitcnt lgkmcnt(0)
	s_barrier
	s_setprio 1
	s_waitcnt lgkmcnt(0)
	v_mfma_f32_16x16x32_bf16 v[124:127], v[128:131], v[176:179], v[124:127]
	v_mfma_f32_16x16x32_bf16 v[120:123], v[136:139], v[176:179], v[120:123]
	v_mfma_f32_16x16x32_bf16 v[116:119], v[128:131], v[192:195], v[116:119]
	v_mfma_f32_16x16x32_bf16 v[112:115], v[136:139], v[192:195], v[112:115]
	v_mfma_f32_16x16x32_bf16 v[108:111], v[128:131], v[200:203], v[108:111]
	v_mfma_f32_16x16x32_bf16 v[100:103], v[136:139], v[200:203], v[100:103]
	v_mfma_f32_16x16x32_bf16 v[88:91], v[128:131], v[208:211], v[88:91]
	v_mfma_f32_16x16x32_bf16 v[80:83], v[136:139], v[208:211], v[80:83]
	v_mfma_f32_16x16x32_bf16 v[124:127], v[132:135], v[188:191], v[124:127]
	v_mfma_f32_16x16x32_bf16 v[120:123], v[140:143], v[188:191], v[120:123]
	v_mfma_f32_16x16x32_bf16 v[116:119], v[132:135], v[196:199], v[116:119]
	v_mfma_f32_16x16x32_bf16 v[112:115], v[140:143], v[196:199], v[112:115]
	v_mfma_f32_16x16x32_bf16 v[108:111], v[132:135], v[204:207], v[108:111]
	v_mfma_f32_16x16x32_bf16 v[100:103], v[140:143], v[204:207], v[100:103]
	v_mfma_f32_16x16x32_bf16 v[88:91], v[132:135], v[216:219], v[88:91]
	v_mfma_f32_16x16x32_bf16 v[80:83], v[140:143], v[216:219], v[80:83]
	s_setprio 0
	s_setprio 1
	v_mfma_f32_16x16x32_bf16 v[104:107], v[144:147], v[176:179], v[104:107]
	v_mfma_f32_16x16x32_bf16 v[96:99], v[168:171], v[176:179], v[96:99]
	v_mfma_f32_16x16x32_bf16 v[92:95], v[144:147], v[192:195], v[92:95]
	v_mfma_f32_16x16x32_bf16 v[84:87], v[168:171], v[192:195], v[84:87]
	v_mfma_f32_16x16x32_bf16 v[76:79], v[144:147], v[200:203], v[76:79]
	v_mfma_f32_16x16x32_bf16 v[72:75], v[168:171], v[200:203], v[72:75]
	v_mfma_f32_16x16x32_bf16 v[68:71], v[144:147], v[208:211], v[68:71]
	v_mfma_f32_16x16x32_bf16 v[64:67], v[168:171], v[208:211], v[64:67]
	v_mfma_f32_16x16x32_bf16 v[104:107], v[164:167], v[188:191], v[104:107]
	v_mfma_f32_16x16x32_bf16 v[96:99], v[172:175], v[188:191], v[96:99]
	v_mfma_f32_16x16x32_bf16 v[92:95], v[164:167], v[196:199], v[92:95]
	v_mfma_f32_16x16x32_bf16 v[84:87], v[172:175], v[196:199], v[84:87]
	v_mfma_f32_16x16x32_bf16 v[76:79], v[164:167], v[204:207], v[76:79]
	v_mfma_f32_16x16x32_bf16 v[72:75], v[172:175], v[204:207], v[72:75]
	v_mfma_f32_16x16x32_bf16 v[68:71], v[164:167], v[216:219], v[68:71]
	v_mfma_f32_16x16x32_bf16 v[64:67], v[172:175], v[216:219], v[64:67]
	s_setprio 0
	s_barrier
	s_add_i32 s22, s45, s24
	v_lshl_add_u64 v[212:213], v[212:213], 0, s[6:7]
	s_mov_b32 m0, s22
	ds_read_b128 v[176:179], v185 offset:49152
	ds_read_b128 v[188:191], v185 offset:50176
	ds_read_b128 v[192:195], v185 offset:51200
	ds_read_b128 v[196:199], v185 offset:52224
	ds_read_b128 v[200:203], v185 offset:53248
	ds_read_b128 v[204:207], v185 offset:54272
	ds_read_b128 v[208:211], v185 offset:55296
	ds_read_b128 v[216:219], v185 offset:56320
	global_load_lds_dwordx4 v[212:213], off
	s_add_i32 m0, s22, 0x2000
	s_add_u32 s20, s20, 0x40080
	v_lshl_add_u64 v[212:213], v[220:221], 0, s[6:7]
	s_addc_u32 s21, s21, 0
	s_add_i32 s22, s46, s24
	global_load_lds_dwordx4 v[212:213], off
	s_mov_b32 m0, s22
	s_nop 0
	global_load_lds_dwordx4 v152, s[20:21]
	s_add_i32 m0, s22, 0x2000
	s_nop 0
	global_load_lds_dwordx4 v148, s[20:21]
	v_lshl_add_u64 v[212:213], v[222:223], 0, s[6:7]
	s_mov_b32 m0, s33
	s_nop 0
	global_load_lds_dwordx4 v[212:213], off
	v_lshl_add_u64 v[212:213], v[224:225], 0, s[6:7]
	s_mov_b32 m0, s34
	s_nop 0
	global_load_lds_dwordx4 v[212:213], off
	s_waitcnt vmcnt(8)
	s_waitcnt lgkmcnt(0)
	s_barrier
	s_setprio 1
	s_waitcnt lgkmcnt(0)
	v_mfma_f32_16x16x32_bf16 v[60:63], v[128:131], v[176:179], v[60:63]
	v_mfma_f32_16x16x32_bf16 v[56:59], v[136:139], v[176:179], v[56:59]
	v_mfma_f32_16x16x32_bf16 v[52:55], v[128:131], v[192:195], v[52:55]
	v_mfma_f32_16x16x32_bf16 v[48:51], v[136:139], v[192:195], v[48:51]
	v_mfma_f32_16x16x32_bf16 v[40:43], v[128:131], v[200:203], v[40:43]
	v_mfma_f32_16x16x32_bf16 v[32:35], v[136:139], v[200:203], v[32:35]
	v_mfma_f32_16x16x32_bf16 v[20:23], v[128:131], v[208:211], v[20:23]
	v_mfma_f32_16x16x32_bf16 v[16:19], v[136:139], v[208:211], v[16:19]
	v_mfma_f32_16x16x32_bf16 v[60:63], v[132:135], v[188:191], v[60:63]
	v_mfma_f32_16x16x32_bf16 v[56:59], v[140:143], v[188:191], v[56:59]
	v_mfma_f32_16x16x32_bf16 v[52:55], v[132:135], v[196:199], v[52:55]
	v_mfma_f32_16x16x32_bf16 v[48:51], v[140:143], v[196:199], v[48:51]
	v_mfma_f32_16x16x32_bf16 v[40:43], v[132:135], v[204:207], v[40:43]
	v_mfma_f32_16x16x32_bf16 v[32:35], v[140:143], v[204:207], v[32:35]
	v_mfma_f32_16x16x32_bf16 v[20:23], v[132:135], v[216:219], v[20:23]
	v_mfma_f32_16x16x32_bf16 v[16:19], v[140:143], v[216:219], v[16:19]
	s_setprio 0
	s_setprio 1
	v_mfma_f32_16x16x32_bf16 v[44:47], v[144:147], v[176:179], v[44:47]
	v_mfma_f32_16x16x32_bf16 v[36:39], v[168:171], v[176:179], v[36:39]
	v_mfma_f32_16x16x32_bf16 v[28:31], v[144:147], v[192:195], v[28:31]
	v_mfma_f32_16x16x32_bf16 v[24:27], v[168:171], v[192:195], v[24:27]
	v_mfma_f32_16x16x32_bf16 v[12:15], v[144:147], v[200:203], v[12:15]
	v_mfma_f32_16x16x32_bf16 v[8:11], v[168:171], v[200:203], v[8:11]
	v_mfma_f32_16x16x32_bf16 v[4:7], v[144:147], v[208:211], v[4:7]
	v_mfma_f32_16x16x32_bf16 v[0:3], v[168:171], v[208:211], v[0:3]
	v_mfma_f32_16x16x32_bf16 v[44:47], v[164:167], v[188:191], v[44:47]
	v_mfma_f32_16x16x32_bf16 v[36:39], v[172:175], v[188:191], v[36:39]
	v_mfma_f32_16x16x32_bf16 v[28:31], v[164:167], v[196:199], v[28:31]
	v_mfma_f32_16x16x32_bf16 v[24:27], v[172:175], v[196:199], v[24:27]
	v_mfma_f32_16x16x32_bf16 v[12:15], v[164:167], v[204:207], v[12:15]
	v_mfma_f32_16x16x32_bf16 v[8:11], v[172:175], v[204:207], v[8:11]
	v_mfma_f32_16x16x32_bf16 v[4:7], v[164:167], v[216:219], v[4:7]
	v_mfma_f32_16x16x32_bf16 v[0:3], v[172:175], v[216:219], v[0:3]
	s_setprio 0
	s_barrier
	s_add_i32 s44, s44, 2
	s_add_u32 s18, s18, 0x100
	s_addc_u32 s19, s19, 0
	s_add_u32 s42, s42, 0x100
	s_addc_u32 s43, s43, 0
	s_cmp_gt_u32 s44, 13
	s_cbranch_scc0 .LBB0_1243
	s_and_b64 vcc, exec, s[8:9]
	s_cbranch_vccz .LBB0_1246
	s_barrier

.LBB0_1325:
	ds_read_b128 v[120:123], v209
	ds_read_b128 v[128:131], v209 offset:1024
	ds_read_b128 v[136:139], v209 offset:2048
	ds_read_b128 v[140:143], v209 offset:3072
	ds_read_b128 v[144:147], v210
	ds_read_b128 v[148:151], v210 offset:1024
	ds_read_b128 v[152:155], v210 offset:2048
	ds_read_b128 v[156:159], v210 offset:3072
	s_add_u32 s4, s22, 0x100
	s_addc_u32 s5, s23, 0
	s_cmp_eq_u32 s47, 40
	s_cselect_b32 s27, s17, s5
	s_cselect_b32 s26, s16, s4
	s_cselect_b32 s25, s19, s46
	s_cselect_b32 s24, s18, s21
	s_add_i32 m0, s29, 0xc000
	ds_read_b128 v[160:163], v211
	ds_read_b128 v[164:167], v211 offset:1024
	ds_read_b128 v[184:187], v211 offset:2048
	ds_read_b128 v[188:191], v211 offset:3072
	ds_read_b128 v[192:195], v211 offset:4096
	ds_read_b128 v[196:199], v211 offset:5120
	ds_read_b128 v[200:203], v211 offset:6144
	ds_read_b128 v[216:219], v211 offset:7168
	global_load_lds_dwordx4 v176, s[22:23]
	s_add_i32 m0, s29, 0xe000
	s_nop 0
	global_load_lds_dwordx4 v178, s[22:23]
	s_waitcnt vmcnt(8)
	s_waitcnt lgkmcnt(0)
	s_barrier
	s_setprio 1
	s_waitcnt lgkmcnt(0)
	v_mfma_f32_16x16x32_bf16 v[132:135], v[120:123], v[160:163], v[132:135]
	v_mfma_f32_16x16x32_bf16 v[124:127], v[136:139], v[160:163], v[124:127]
	v_mfma_f32_16x16x32_bf16 v[108:111], v[120:123], v[184:187], v[108:111]
	v_mfma_f32_16x16x32_bf16 v[104:107], v[136:139], v[184:187], v[104:107]
	v_mfma_f32_16x16x32_bf16 v[92:95], v[120:123], v[192:195], v[92:95]
	v_mfma_f32_16x16x32_bf16 v[88:91], v[136:139], v[192:195], v[88:91]
	v_mfma_f32_16x16x32_bf16 v[76:79], v[120:123], v[200:203], v[76:79]
	v_mfma_f32_16x16x32_bf16 v[72:75], v[136:139], v[200:203], v[72:75]
	v_mfma_f32_16x16x32_bf16 v[132:135], v[128:131], v[164:167], v[132:135]
	v_mfma_f32_16x16x32_bf16 v[124:127], v[140:143], v[164:167], v[124:127]
	v_mfma_f32_16x16x32_bf16 v[108:111], v[128:131], v[188:191], v[108:111]
	v_mfma_f32_16x16x32_bf16 v[104:107], v[140:143], v[188:191], v[104:107]
	v_mfma_f32_16x16x32_bf16 v[92:95], v[128:131], v[196:199], v[92:95]
	v_mfma_f32_16x16x32_bf16 v[88:91], v[140:143], v[196:199], v[88:91]
	v_mfma_f32_16x16x32_bf16 v[76:79], v[128:131], v[216:219], v[76:79]
	v_mfma_f32_16x16x32_bf16 v[72:75], v[140:143], v[216:219], v[72:75]
	s_setprio 0
	s_setprio 1
	v_mfma_f32_16x16x32_bf16 v[116:119], v[144:147], v[160:163], v[116:119]
	v_mfma_f32_16x16x32_bf16 v[112:115], v[152:155], v[160:163], v[112:115]
	v_mfma_f32_16x16x32_bf16 v[100:103], v[144:147], v[184:187], v[100:103]
	v_mfma_f32_16x16x32_bf16 v[96:99], v[152:155], v[184:187], v[96:99]
	v_mfma_f32_16x16x32_bf16 v[84:87], v[144:147], v[192:195], v[84:87]
	v_mfma_f32_16x16x32_bf16 v[80:83], v[152:155], v[192:195], v[80:83]
	v_mfma_f32_16x16x32_bf16 v[68:71], v[144:147], v[200:203], v[68:71]
	v_mfma_f32_16x16x32_bf16 v[64:67], v[152:155], v[200:203], v[64:67]
	v_mfma_f32_16x16x32_bf16 v[116:119], v[148:151], v[164:167], v[116:119]
	v_mfma_f32_16x16x32_bf16 v[112:115], v[156:159], v[164:167], v[112:115]
	v_mfma_f32_16x16x32_bf16 v[100:103], v[148:151], v[188:191], v[100:103]
	v_mfma_f32_16x16x32_bf16 v[96:99], v[156:159], v[188:191], v[96:99]
	v_mfma_f32_16x16x32_bf16 v[84:87], v[148:151], v[196:199], v[84:87]
	v_mfma_f32_16x16x32_bf16 v[80:83], v[156:159], v[196:199], v[80:83]
	v_mfma_f32_16x16x32_bf16 v[68:71], v[148:151], v[216:219], v[68:71]
	v_mfma_f32_16x16x32_bf16 v[64:67], v[156:159], v[216:219], v[64:67]
	s_setprio 0
	s_barrier
	s_add_i32 s22, s41, s28
	v_lshl_add_u64 v[220:221], s[24:25], 0, v[170:171]
	s_mov_b32 m0, s22
	ds_read_b128 v[160:163], v211 offset:16384
	ds_read_b128 v[164:167], v211 offset:17408
	ds_read_b128 v[184:187], v211 offset:18432
	ds_read_b128 v[188:191], v211 offset:19456
	ds_read_b128 v[192:195], v211 offset:20480
	ds_read_b128 v[196:199], v211 offset:21504
	ds_read_b128 v[200:203], v211 offset:22528
	ds_read_b128 v[216:219], v211 offset:23552
	global_load_lds_dwordx4 v[220:221], off
	s_add_i32 m0, s22, 0x2000
	s_add_u32 s22, s24, 0xb0000
	v_lshl_add_u64 v[222:223], s[24:25], 0, v[174:175]
	s_addc_u32 s23, s25, 0
	s_add_i32 s48, s42, s28
	global_load_lds_dwordx4 v[222:223], off
	s_mov_b32 m0, s48
	v_lshl_add_u64 v[226:227], s[26:27], 0, v[172:173]
	global_load_lds_dwordx4 v170, s[22:23]
	s_add_i32 m0, s48, 0x2000
	s_nop 0
	global_load_lds_dwordx4 v174, s[22:23]
	v_lshl_add_u64 v[224:225], s[26:27], 0, v[168:169]
	s_mov_b32 m0, s29
	s_nop 0
	global_load_lds_dwordx4 v[224:225], off
	s_mov_b32 m0, s30
	s_nop 0
	global_load_lds_dwordx4 v[226:227], off
	s_waitcnt vmcnt(8)
	s_waitcnt lgkmcnt(0)
	s_barrier
	s_setprio 1
	s_waitcnt lgkmcnt(0)
	v_mfma_f32_16x16x32_bf16 v[60:63], v[120:123], v[160:163], v[60:63]
	v_mfma_f32_16x16x32_bf16 v[56:59], v[136:139], v[160:163], v[56:59]
	v_mfma_f32_16x16x32_bf16 v[44:47], v[120:123], v[184:187], v[44:47]
	v_mfma_f32_16x16x32_bf16 v[40:43], v[136:139], v[184:187], v[40:43]
	v_mfma_f32_16x16x32_bf16 v[28:31], v[120:123], v[192:195], v[28:31]
	v_mfma_f32_16x16x32_bf16 v[24:27], v[136:139], v[192:195], v[24:27]
	v_mfma_f32_16x16x32_bf16 v[12:15], v[120:123], v[200:203], v[12:15]
	v_mfma_f32_16x16x32_bf16 v[8:11], v[136:139], v[200:203], v[8:11]
	v_mfma_f32_16x16x32_bf16 v[60:63], v[128:131], v[164:167], v[60:63]
	v_mfma_f32_16x16x32_bf16 v[56:59], v[140:143], v[164:167], v[56:59]
	v_mfma_f32_16x16x32_bf16 v[44:47], v[128:131], v[188:191], v[44:47]
	v_mfma_f32_16x16x32_bf16 v[40:43], v[140:143], v[188:191], v[40:43]
	v_mfma_f32_16x16x32_bf16 v[28:31], v[128:131], v[196:199], v[28:31]
	v_mfma_f32_16x16x32_bf16 v[24:27], v[140:143], v[196:199], v[24:27]
	v_mfma_f32_16x16x32_bf16 v[12:15], v[128:131], v[216:219], v[12:15]
	v_mfma_f32_16x16x32_bf16 v[8:11], v[140:143], v[216:219], v[8:11]
	s_setprio 0
	s_setprio 1
	v_mfma_f32_16x16x32_bf16 v[52:55], v[144:147], v[160:163], v[52:55]
	v_mfma_f32_16x16x32_bf16 v[48:51], v[152:155], v[160:163], v[48:51]
	v_mfma_f32_16x16x32_bf16 v[36:39], v[144:147], v[184:187], v[36:39]
	v_mfma_f32_16x16x32_bf16 v[32:35], v[152:155], v[184:187], v[32:35]
	v_mfma_f32_16x16x32_bf16 v[20:23], v[144:147], v[192:195], v[20:23]
	v_mfma_f32_16x16x32_bf16 v[16:19], v[152:155], v[192:195], v[16:19]
	v_mfma_f32_16x16x32_bf16 v[4:7], v[144:147], v[200:203], v[4:7]
	v_mfma_f32_16x16x32_bf16 v[0:3], v[152:155], v[200:203], v[0:3]
	v_mfma_f32_16x16x32_bf16 v[52:55], v[148:151], v[164:167], v[52:55]
	v_mfma_f32_16x16x32_bf16 v[48:51], v[156:159], v[164:167], v[48:51]
	v_mfma_f32_16x16x32_bf16 v[36:39], v[148:151], v[188:191], v[36:39]
	v_mfma_f32_16x16x32_bf16 v[32:35], v[156:159], v[188:191], v[32:35]
	v_mfma_f32_16x16x32_bf16 v[20:23], v[148:151], v[196:199], v[20:23]
	v_mfma_f32_16x16x32_bf16 v[16:19], v[156:159], v[196:199], v[16:19]
	v_mfma_f32_16x16x32_bf16 v[4:7], v[148:151], v[216:219], v[4:7]
	v_mfma_f32_16x16x32_bf16 v[0:3], v[156:159], v[216:219], v[0:3]
	s_setprio 0
	s_barrier
	s_add_i32 s48, 0, 0x18000
	s_add_i32 s49, 0, 0x1c000
	v_add_u32_e32 v140, s48, v205
	v_add_u32_e32 v156, s49, v205
	ds_read_b128 v[120:123], v140
	ds_read_b128 v[128:131], v140 offset:1024
	ds_read_b128 v[136:139], v140 offset:2048
	ds_read_b128 v[140:143], v140 offset:3072
	ds_read_b128 v[144:147], v156
	ds_read_b128 v[148:151], v156 offset:1024
	ds_read_b128 v[152:155], v156 offset:2048
	ds_read_b128 v[156:159], v156 offset:3072
	s_add_u32 s22, s26, 0xb0000
	s_addc_u32 s23, s27, 0
	s_mov_b32 m0, s31
	ds_read_b128 v[160:163], v211 offset:32768
	ds_read_b128 v[164:167], v211 offset:33792
	ds_read_b128 v[184:187], v211 offset:34816
	ds_read_b128 v[188:191], v211 offset:35840
	ds_read_b128 v[192:195], v211 offset:36864
	ds_read_b128 v[196:199], v211 offset:37888
	ds_read_b128 v[200:203], v211 offset:38912
	ds_read_b128 v[216:219], v211 offset:39936
	global_load_lds_dwordx4 v168, s[22:23]
	s_mov_b32 m0, s33
	s_nop 0
	global_load_lds_dwordx4 v172, s[22:23]
	s_waitcnt vmcnt(8)
	s_waitcnt lgkmcnt(0)
	s_barrier
	s_setprio 1
	s_waitcnt lgkmcnt(0)
	v_mfma_f32_16x16x32_bf16 v[132:135], v[120:123], v[160:163], v[132:135]
	v_mfma_f32_16x16x32_bf16 v[124:127], v[136:139], v[160:163], v[124:127]
	v_mfma_f32_16x16x32_bf16 v[108:111], v[120:123], v[184:187], v[108:111]
	v_mfma_f32_16x16x32_bf16 v[104:107], v[136:139], v[184:187], v[104:107]
	v_mfma_f32_16x16x32_bf16 v[92:95], v[120:123], v[192:195], v[92:95]
	v_mfma_f32_16x16x32_bf16 v[88:91], v[136:139], v[192:195], v[88:91]
	v_mfma_f32_16x16x32_bf16 v[76:79], v[120:123], v[200:203], v[76:79]
	v_mfma_f32_16x16x32_bf16 v[72:75], v[136:139], v[200:203], v[72:75]
	v_mfma_f32_16x16x32_bf16 v[132:135], v[128:131], v[164:167], v[132:135]
	v_mfma_f32_16x16x32_bf16 v[124:127], v[140:143], v[164:167], v[124:127]
	v_mfma_f32_16x16x32_bf16 v[108:111], v[128:131], v[188:191], v[108:111]
	v_mfma_f32_16x16x32_bf16 v[104:107], v[140:143], v[188:191], v[104:107]
	v_mfma_f32_16x16x32_bf16 v[92:95], v[128:131], v[196:199], v[92:95]
	v_mfma_f32_16x16x32_bf16 v[88:91], v[140:143], v[196:199], v[88:91]
	v_mfma_f32_16x16x32_bf16 v[76:79], v[128:131], v[216:219], v[76:79]
	v_mfma_f32_16x16x32_bf16 v[72:75], v[140:143], v[216:219], v[72:75]
	s_setprio 0
	s_setprio 1
	v_mfma_f32_16x16x32_bf16 v[116:119], v[144:147], v[160:163], v[116:119]
	v_mfma_f32_16x16x32_bf16 v[112:115], v[152:155], v[160:163], v[112:115]
	v_mfma_f32_16x16x32_bf16 v[100:103], v[144:147], v[184:187], v[100:103]
	v_mfma_f32_16x16x32_bf16 v[96:99], v[152:155], v[184:187], v[96:99]
	v_mfma_f32_16x16x32_bf16 v[84:87], v[144:147], v[192:195], v[84:87]
	v_mfma_f32_16x16x32_bf16 v[80:83], v[152:155], v[192:195], v[80:83]
	v_mfma_f32_16x16x32_bf16 v[68:71], v[144:147], v[200:203], v[68:71]
	v_mfma_f32_16x16x32_bf16 v[64:67], v[152:155], v[200:203], v[64:67]
	v_mfma_f32_16x16x32_bf16 v[116:119], v[148:151], v[164:167], v[116:119]
	v_mfma_f32_16x16x32_bf16 v[112:115], v[156:159], v[164:167], v[112:115]
	v_mfma_f32_16x16x32_bf16 v[100:103], v[148:151], v[188:191], v[100:103]
	v_mfma_f32_16x16x32_bf16 v[96:99], v[156:159], v[188:191], v[96:99]
	v_mfma_f32_16x16x32_bf16 v[84:87], v[148:151], v[196:199], v[84:87]
	v_mfma_f32_16x16x32_bf16 v[80:83], v[156:159], v[196:199], v[80:83]
	v_mfma_f32_16x16x32_bf16 v[68:71], v[148:151], v[216:219], v[68:71]
	v_mfma_f32_16x16x32_bf16 v[64:67], v[156:159], v[216:219], v[64:67]
	s_setprio 0
	s_barrier
	s_add_i32 s22, s48, s28
	v_lshl_add_u64 v[220:221], v[220:221], 0, s[8:9]
	s_mov_b32 m0, s22
	ds_read_b128 v[160:163], v211 offset:49152
	ds_read_b128 v[164:167], v211 offset:50176
	ds_read_b128 v[184:187], v211 offset:51200
	ds_read_b128 v[188:191], v211 offset:52224
	ds_read_b128 v[192:195], v211 offset:53248
	ds_read_b128 v[196:199], v211 offset:54272
	ds_read_b128 v[200:203], v211 offset:55296
	ds_read_b128 v[216:219], v211 offset:56320
	global_load_lds_dwordx4 v[220:221], off
	s_add_i32 m0, s22, 0x2000
	s_add_u32 s22, s24, 0xb0080
	v_lshl_add_u64 v[220:221], v[222:223], 0, s[8:9]
	s_addc_u32 s23, s25, 0
	s_add_i32 s24, s49, s28
	global_load_lds_dwordx4 v[220:221], off
	s_mov_b32 m0, s24
	s_nop 0
	global_load_lds_dwordx4 v170, s[22:23]
	s_add_i32 m0, s24, 0x2000
	s_nop 0
	global_load_lds_dwordx4 v174, s[22:23]
	v_lshl_add_u64 v[220:221], v[224:225], 0, s[8:9]
	s_mov_b32 m0, s37
	s_nop 0
	global_load_lds_dwordx4 v[220:221], off
	v_lshl_add_u64 v[220:221], v[226:227], 0, s[8:9]
	s_mov_b32 m0, s38
	s_nop 0
	global_load_lds_dwordx4 v[220:221], off
	s_waitcnt vmcnt(8)
	s_waitcnt lgkmcnt(0)
	s_barrier
	s_setprio 1
	s_waitcnt lgkmcnt(0)
	v_mfma_f32_16x16x32_bf16 v[60:63], v[120:123], v[160:163], v[60:63]
	v_mfma_f32_16x16x32_bf16 v[56:59], v[136:139], v[160:163], v[56:59]
	v_mfma_f32_16x16x32_bf16 v[44:47], v[120:123], v[184:187], v[44:47]
	v_mfma_f32_16x16x32_bf16 v[40:43], v[136:139], v[184:187], v[40:43]
	v_mfma_f32_16x16x32_bf16 v[28:31], v[120:123], v[192:195], v[28:31]
	v_mfma_f32_16x16x32_bf16 v[24:27], v[136:139], v[192:195], v[24:27]
	v_mfma_f32_16x16x32_bf16 v[12:15], v[120:123], v[200:203], v[12:15]
	v_mfma_f32_16x16x32_bf16 v[8:11], v[136:139], v[200:203], v[8:11]
	v_mfma_f32_16x16x32_bf16 v[60:63], v[128:131], v[164:167], v[60:63]
	v_mfma_f32_16x16x32_bf16 v[56:59], v[140:143], v[164:167], v[56:59]
	v_mfma_f32_16x16x32_bf16 v[44:47], v[128:131], v[188:191], v[44:47]
	v_mfma_f32_16x16x32_bf16 v[40:43], v[140:143], v[188:191], v[40:43]
	v_mfma_f32_16x16x32_bf16 v[28:31], v[128:131], v[196:199], v[28:31]
	v_mfma_f32_16x16x32_bf16 v[24:27], v[140:143], v[196:199], v[24:27]
	v_mfma_f32_16x16x32_bf16 v[12:15], v[128:131], v[216:219], v[12:15]
	v_mfma_f32_16x16x32_bf16 v[8:11], v[140:143], v[216:219], v[8:11]
	s_setprio 0
	s_setprio 1
	v_mfma_f32_16x16x32_bf16 v[52:55], v[144:147], v[160:163], v[52:55]
	v_mfma_f32_16x16x32_bf16 v[48:51], v[152:155], v[160:163], v[48:51]
	v_mfma_f32_16x16x32_bf16 v[36:39], v[144:147], v[184:187], v[36:39]
	v_mfma_f32_16x16x32_bf16 v[32:35], v[152:155], v[184:187], v[32:35]
	v_mfma_f32_16x16x32_bf16 v[20:23], v[144:147], v[192:195], v[20:23]
	v_mfma_f32_16x16x32_bf16 v[16:19], v[152:155], v[192:195], v[16:19]
	v_mfma_f32_16x16x32_bf16 v[4:7], v[144:147], v[200:203], v[4:7]
	v_mfma_f32_16x16x32_bf16 v[0:3], v[152:155], v[200:203], v[0:3]
	v_mfma_f32_16x16x32_bf16 v[52:55], v[148:151], v[164:167], v[52:55]
	v_mfma_f32_16x16x32_bf16 v[48:51], v[156:159], v[164:167], v[48:51]
	v_mfma_f32_16x16x32_bf16 v[36:39], v[148:151], v[188:191], v[36:39]
	v_mfma_f32_16x16x32_bf16 v[32:35], v[156:159], v[188:191], v[32:35]
	v_mfma_f32_16x16x32_bf16 v[20:23], v[148:151], v[196:199], v[20:23]
	v_mfma_f32_16x16x32_bf16 v[16:19], v[156:159], v[196:199], v[16:19]
	v_mfma_f32_16x16x32_bf16 v[4:7], v[148:151], v[216:219], v[4:7]
	v_mfma_f32_16x16x32_bf16 v[0:3], v[156:159], v[216:219], v[0:3]
	s_setprio 0
	s_barrier
	s_add_i32 s47, s47, 2
	s_add_u32 s21, s21, 0x100
	s_addc_u32 s46, s46, 0
	s_cmp_gt_u32 s47, 41
	s_mov_b64 s[22:23], s[4:5]
	s_cbranch_scc0 .LBB0_1325
	s_and_b64 vcc, exec, s[10:11]
	s_cbranch_vccz .LBB0_1328
	s_barrier
